# GEMM K-loops: deleted the back-to-back s_setprio 0 / s_setprio 1 blips inside each 32-MFMA block (outer raise/lower kept)
# baseline (speedup 1.0000x reference)
.LBB0_288:
	s_add_u32 s12, s4, 0xfff80080
	s_addc_u32 s38, s5, -1
	s_add_i32 s50, 0, 0x10000
	s_cmp_eq_u32 s49, 28
	s_cselect_b32 s47, s10, s38
	s_cselect_b32 s46, s28, s12
	v_add_u32_e32 v0, s50, v173
	s_cselect_b32 s39, s29, s48
	s_cselect_b32 s38, s43, s45
	s_add_i32 s12, 0, 0x14000
	ds_read_b128 v[50:53], v0
	ds_read_b128 v[54:57], v0 offset:1024
	ds_read_b128 v[156:159], v0 offset:2048
	ds_read_b128 v[160:163], v0 offset:3072
	v_add_u32_e32 v0, s12, v173
	ds_read_b128 v[164:167], v0
	ds_read_b128 v[168:171], v0 offset:1024
	ds_read_b128 v[190:193], v0 offset:2048
	ds_read_b128 v[194:197], v0 offset:3072
	v_lshl_add_u64 v[186:187], s[4:5], 0, v[150:151]
	s_add_i32 m0, s20, 0xc000
	ds_read_b128 v[198:201], v184
	ds_read_b128 v[202:205], v184 offset:1024
	ds_read_b128 v[206:209], v184 offset:2048
	ds_read_b128 v[232:235], v184 offset:3072
	ds_read_b128 v[236:239], v184 offset:4096
	ds_read_b128 v[240:243], v184 offset:5120
	ds_read_b128 v[244:247], v184 offset:6144
	ds_read_b128 v[248:251], v184 offset:7168
	global_load_lds_dwordx4 v[186:187], off
	v_lshl_add_u64 v[186:187], s[4:5], 0, v[152:153]
	s_add_i32 m0, s20, 0xe000
	s_nop 0
	global_load_lds_dwordx4 v[186:187], off
	s_waitcnt vmcnt(8)
	s_waitcnt lgkmcnt(0)
	s_barrier
	s_setprio 1
	s_waitcnt lgkmcnt(0)
	v_mfma_f32_16x16x32_bf16 v[134:137], v[50:53], v[198:201], v[134:137]
	v_mfma_f32_16x16x32_bf16 v[130:133], v[156:159], v[198:201], v[130:133]
	v_mfma_f32_16x16x32_bf16 v[118:121], v[50:53], v[206:209], v[118:121]
	v_mfma_f32_16x16x32_bf16 v[114:117], v[156:159], v[206:209], v[114:117]
	v_mfma_f32_16x16x32_bf16 v[102:105], v[50:53], v[236:239], v[102:105]
	v_mfma_f32_16x16x32_bf16 v[98:101], v[156:159], v[236:239], v[98:101]
	v_mfma_f32_16x16x32_bf16 v[86:89], v[50:53], v[244:247], v[86:89]
	v_mfma_f32_16x16x32_bf16 v[82:85], v[156:159], v[244:247], v[82:85]
	v_mfma_f32_16x16x32_bf16 v[134:137], v[54:57], v[202:205], v[134:137]
	v_mfma_f32_16x16x32_bf16 v[130:133], v[160:163], v[202:205], v[130:133]
	v_mfma_f32_16x16x32_bf16 v[118:121], v[54:57], v[232:235], v[118:121]
	v_mfma_f32_16x16x32_bf16 v[114:117], v[160:163], v[232:235], v[114:117]
	v_mfma_f32_16x16x32_bf16 v[102:105], v[54:57], v[240:243], v[102:105]
	v_mfma_f32_16x16x32_bf16 v[98:101], v[160:163], v[240:243], v[98:101]
	v_mfma_f32_16x16x32_bf16 v[86:89], v[54:57], v[248:251], v[86:89]
	v_mfma_f32_16x16x32_bf16 v[82:85], v[160:163], v[248:251], v[82:85]
	v_mfma_f32_16x16x32_bf16 v[126:129], v[164:167], v[198:201], v[126:129]
	v_mfma_f32_16x16x32_bf16 v[122:125], v[190:193], v[198:201], v[122:125]
	v_mfma_f32_16x16x32_bf16 v[110:113], v[164:167], v[206:209], v[110:113]
	v_mfma_f32_16x16x32_bf16 v[106:109], v[190:193], v[206:209], v[106:109]
	v_mfma_f32_16x16x32_bf16 v[94:97], v[164:167], v[236:239], v[94:97]
	v_mfma_f32_16x16x32_bf16 v[90:93], v[190:193], v[236:239], v[90:93]
	v_mfma_f32_16x16x32_bf16 v[78:81], v[164:167], v[244:247], v[78:81]
	v_mfma_f32_16x16x32_bf16 v[74:77], v[190:193], v[244:247], v[74:77]
	v_mfma_f32_16x16x32_bf16 v[126:129], v[168:171], v[202:205], v[126:129]
	v_mfma_f32_16x16x32_bf16 v[122:125], v[194:197], v[202:205], v[122:125]
	v_mfma_f32_16x16x32_bf16 v[110:113], v[168:171], v[232:235], v[110:113]
	v_mfma_f32_16x16x32_bf16 v[106:109], v[194:197], v[232:235], v[106:109]
	v_mfma_f32_16x16x32_bf16 v[94:97], v[168:171], v[240:243], v[94:97]
	v_mfma_f32_16x16x32_bf16 v[90:93], v[194:197], v[240:243], v[90:93]
	v_mfma_f32_16x16x32_bf16 v[78:81], v[168:171], v[248:251], v[78:81]
	v_mfma_f32_16x16x32_bf16 v[74:77], v[194:197], v[248:251], v[74:77]
	s_setprio 0
	s_barrier
	s_add_i32 s50, s50, s8
	v_lshl_add_u64 v[186:187], s[38:39], 0, v[140:141]
	s_mov_b32 m0, s50
	ds_read_b128 v[198:201], v184 offset:16384
	ds_read_b128 v[202:205], v184 offset:17408
	ds_read_b128 v[206:209], v184 offset:18432
	ds_read_b128 v[232:235], v184 offset:19456
	ds_read_b128 v[236:239], v184 offset:20480
	ds_read_b128 v[240:243], v184 offset:21504
	ds_read_b128 v[244:247], v184 offset:22528
	ds_read_b128 v[248:251], v184 offset:23552
	global_load_lds_dwordx4 v[186:187], off
	s_add_i32 m0, s50, 0x2000
	s_add_u32 s50, s38, 0x80000
	v_lshl_add_u64 v[188:189], s[38:39], 0, v[144:145]
	s_addc_u32 s51, s39, 0
	s_add_i32 s12, s12, s8
	global_load_lds_dwordx4 v[188:189], off
	v_lshl_add_u64 v[218:219], s[50:51], 0, v[140:141]
	s_mov_b32 m0, s12
	v_lshl_add_u64 v[220:221], s[46:47], 0, v[142:143]
	global_load_lds_dwordx4 v[218:219], off
	v_lshl_add_u64 v[218:219], s[50:51], 0, v[144:145]
	s_add_i32 m0, s12, 0x2000
	s_nop 0
	global_load_lds_dwordx4 v[218:219], off
	v_lshl_add_u64 v[218:219], s[46:47], 0, v[138:139]
	s_mov_b32 m0, s20
	s_nop 0
	global_load_lds_dwordx4 v[218:219], off
	s_mov_b32 m0, s21
	s_nop 0
	global_load_lds_dwordx4 v[220:221], off
	s_waitcnt vmcnt(8)
	s_waitcnt lgkmcnt(0)
	s_barrier
	s_setprio 1
	s_waitcnt lgkmcnt(0)
	v_mfma_f32_16x16x32_bf16 v[70:73], v[50:53], v[198:201], v[70:73]
	v_mfma_f32_16x16x32_bf16 v[66:69], v[156:159], v[198:201], v[66:69]
	v_mfma_f32_16x16x32_bf16 v[46:49], v[50:53], v[206:209], v[46:49]
	v_mfma_f32_16x16x32_bf16 v[42:45], v[156:159], v[206:209], v[42:45]
	v_mfma_f32_16x16x32_bf16 v[30:33], v[50:53], v[236:239], v[30:33]
	v_mfma_f32_16x16x32_bf16 v[26:29], v[156:159], v[236:239], v[26:29]
	v_mfma_f32_16x16x32_bf16 v[14:17], v[50:53], v[244:247], v[14:17]
	v_mfma_f32_16x16x32_bf16 v[10:13], v[156:159], v[244:247], v[10:13]
	v_mfma_f32_16x16x32_bf16 v[70:73], v[54:57], v[202:205], v[70:73]
	v_mfma_f32_16x16x32_bf16 v[66:69], v[160:163], v[202:205], v[66:69]
	v_mfma_f32_16x16x32_bf16 v[46:49], v[54:57], v[232:235], v[46:49]
	v_mfma_f32_16x16x32_bf16 v[42:45], v[160:163], v[232:235], v[42:45]
	v_mfma_f32_16x16x32_bf16 v[30:33], v[54:57], v[240:243], v[30:33]
	v_mfma_f32_16x16x32_bf16 v[26:29], v[160:163], v[240:243], v[26:29]
	v_mfma_f32_16x16x32_bf16 v[14:17], v[54:57], v[248:251], v[14:17]
	v_mfma_f32_16x16x32_bf16 v[10:13], v[160:163], v[248:251], v[10:13]
	v_mfma_f32_16x16x32_bf16 v[38:41], v[164:167], v[206:209], v[38:41]
	v_mfma_f32_16x16x32_bf16 v[34:37], v[190:193], v[206:209], v[34:37]
	v_mfma_f32_16x16x32_bf16 v[22:25], v[164:167], v[236:239], v[22:25]
	v_mfma_f32_16x16x32_bf16 v[18:21], v[190:193], v[236:239], v[18:21]
	v_mfma_f32_16x16x32_bf16 v[6:9], v[164:167], v[244:247], v[6:9]
	v_mfma_f32_16x16x32_bf16 v[2:5], v[190:193], v[244:247], v[2:5]
	v_mfma_f32_16x16x32_bf16 v[50:53], v[164:167], v[198:201], v[62:65]
	v_mfma_f32_16x16x32_bf16 v[54:57], v[190:193], v[198:201], v[58:61]
	v_mfma_f32_16x16x32_bf16 v[38:41], v[168:171], v[232:235], v[38:41]
	v_mfma_f32_16x16x32_bf16 v[34:37], v[194:197], v[232:235], v[34:37]
	v_mfma_f32_16x16x32_bf16 v[22:25], v[168:171], v[240:243], v[22:25]
	v_mfma_f32_16x16x32_bf16 v[18:21], v[194:197], v[240:243], v[18:21]
	v_mfma_f32_16x16x32_bf16 v[6:9], v[168:171], v[248:251], v[6:9]
	v_mfma_f32_16x16x32_bf16 v[2:5], v[194:197], v[248:251], v[2:5]
	v_mfma_f32_16x16x32_bf16 v[50:53], v[168:171], v[202:205], v[50:53]
	v_mfma_f32_16x16x32_bf16 v[54:57], v[194:197], v[202:205], v[54:57]
	s_setprio 0
	s_barrier
	s_add_i32 s12, 0, 0x18000
	v_add_u32_e32 v0, s12, v173
	s_add_i32 s50, 0, 0x1c000
	ds_read_b128 v[58:61], v0
	ds_read_b128 v[62:65], v0 offset:1024
	ds_read_b128 v[156:159], v0 offset:2048
	ds_read_b128 v[160:163], v0 offset:3072
	v_add_u32_e32 v0, s50, v173
	ds_read_b128 v[164:167], v0
	ds_read_b128 v[168:171], v0 offset:1024
	ds_read_b128 v[190:193], v0 offset:2048
	ds_read_b128 v[194:197], v0 offset:3072
	s_add_u32 s46, s46, 0x80000
	s_addc_u32 s47, s47, 0
	s_mov_b32 m0, s22
	v_lshl_add_u64 v[222:223], s[46:47], 0, v[138:139]
	ds_read_b128 v[198:201], v184 offset:32768
	ds_read_b128 v[202:205], v184 offset:33792
	ds_read_b128 v[206:209], v184 offset:34816
	ds_read_b128 v[232:235], v184 offset:35840
	ds_read_b128 v[236:239], v184 offset:36864
	ds_read_b128 v[240:243], v184 offset:37888
	ds_read_b128 v[244:247], v184 offset:38912
	ds_read_b128 v[248:251], v184 offset:39936
	global_load_lds_dwordx4 v[222:223], off
	v_lshl_add_u64 v[222:223], s[46:47], 0, v[142:143]
	s_mov_b32 m0, s23
	s_nop 0
	global_load_lds_dwordx4 v[222:223], off
	s_waitcnt vmcnt(8)
	s_waitcnt lgkmcnt(0)
	s_barrier
	s_setprio 1
	s_waitcnt lgkmcnt(0)
	v_mfma_f32_16x16x32_bf16 v[134:137], v[58:61], v[198:201], v[134:137]
	v_mfma_f32_16x16x32_bf16 v[130:133], v[156:159], v[198:201], v[130:133]
	v_mfma_f32_16x16x32_bf16 v[118:121], v[58:61], v[206:209], v[118:121]
	v_mfma_f32_16x16x32_bf16 v[114:117], v[156:159], v[206:209], v[114:117]
	v_mfma_f32_16x16x32_bf16 v[102:105], v[58:61], v[236:239], v[102:105]
	v_mfma_f32_16x16x32_bf16 v[98:101], v[156:159], v[236:239], v[98:101]
	v_mfma_f32_16x16x32_bf16 v[86:89], v[58:61], v[244:247], v[86:89]
	v_mfma_f32_16x16x32_bf16 v[82:85], v[156:159], v[244:247], v[82:85]
	v_mfma_f32_16x16x32_bf16 v[134:137], v[62:65], v[202:205], v[134:137]
	v_mfma_f32_16x16x32_bf16 v[130:133], v[160:163], v[202:205], v[130:133]
	v_mfma_f32_16x16x32_bf16 v[118:121], v[62:65], v[232:235], v[118:121]
	v_mfma_f32_16x16x32_bf16 v[114:117], v[160:163], v[232:235], v[114:117]
	v_mfma_f32_16x16x32_bf16 v[102:105], v[62:65], v[240:243], v[102:105]
	v_mfma_f32_16x16x32_bf16 v[98:101], v[160:163], v[240:243], v[98:101]
	v_mfma_f32_16x16x32_bf16 v[86:89], v[62:65], v[248:251], v[86:89]
	v_mfma_f32_16x16x32_bf16 v[82:85], v[160:163], v[248:251], v[82:85]
	v_mfma_f32_16x16x32_bf16 v[126:129], v[164:167], v[198:201], v[126:129]
	v_mfma_f32_16x16x32_bf16 v[122:125], v[190:193], v[198:201], v[122:125]
	v_mfma_f32_16x16x32_bf16 v[110:113], v[164:167], v[206:209], v[110:113]
	v_mfma_f32_16x16x32_bf16 v[106:109], v[190:193], v[206:209], v[106:109]
	v_mfma_f32_16x16x32_bf16 v[94:97], v[164:167], v[236:239], v[94:97]
	v_mfma_f32_16x16x32_bf16 v[90:93], v[190:193], v[236:239], v[90:93]
	v_mfma_f32_16x16x32_bf16 v[78:81], v[164:167], v[244:247], v[78:81]
	v_mfma_f32_16x16x32_bf16 v[74:77], v[190:193], v[244:247], v[74:77]
	v_mfma_f32_16x16x32_bf16 v[126:129], v[168:171], v[202:205], v[126:129]
	v_mfma_f32_16x16x32_bf16 v[122:125], v[194:197], v[202:205], v[122:125]
	v_mfma_f32_16x16x32_bf16 v[110:113], v[168:171], v[232:235], v[110:113]
	v_mfma_f32_16x16x32_bf16 v[106:109], v[194:197], v[232:235], v[106:109]
	v_mfma_f32_16x16x32_bf16 v[94:97], v[168:171], v[240:243], v[94:97]
	v_mfma_f32_16x16x32_bf16 v[90:93], v[194:197], v[240:243], v[90:93]
	v_mfma_f32_16x16x32_bf16 v[78:81], v[168:171], v[248:251], v[78:81]
	v_mfma_f32_16x16x32_bf16 v[74:77], v[194:197], v[248:251], v[74:77]
	s_setprio 0
	s_barrier
	s_add_i32 s12, s12, s8
	v_lshl_add_u64 v[186:187], v[186:187], 0, s[16:17]
	s_mov_b32 m0, s12
	ds_read_b128 v[198:201], v184 offset:49152
	ds_read_b128 v[202:205], v184 offset:50176
	ds_read_b128 v[206:209], v184 offset:51200
	ds_read_b128 v[232:235], v184 offset:52224
	ds_read_b128 v[236:239], v184 offset:53248
	ds_read_b128 v[240:243], v184 offset:54272
	ds_read_b128 v[244:247], v184 offset:55296
	ds_read_b128 v[248:251], v184 offset:56320
	global_load_lds_dwordx4 v[186:187], off
	s_add_i32 m0, s12, 0x2000
	s_add_u32 s38, s38, 0x80080
	v_lshl_add_u64 v[186:187], v[188:189], 0, s[16:17]
	s_addc_u32 s39, s39, 0
	s_add_i32 s12, s50, s8
	global_load_lds_dwordx4 v[186:187], off
	v_lshl_add_u64 v[186:187], s[38:39], 0, v[140:141]
	s_mov_b32 m0, s12
	s_nop 0
	global_load_lds_dwordx4 v[186:187], off
	v_lshl_add_u64 v[186:187], s[38:39], 0, v[144:145]
	s_add_i32 m0, s12, 0x2000
	s_nop 0
	global_load_lds_dwordx4 v[186:187], off
	v_lshl_add_u64 v[186:187], v[218:219], 0, s[16:17]
	s_mov_b32 m0, s27
	s_nop 0
	global_load_lds_dwordx4 v[186:187], off
	v_lshl_add_u64 v[186:187], v[220:221], 0, s[16:17]
	s_mov_b32 m0, s33
	s_nop 0
	global_load_lds_dwordx4 v[186:187], off
	s_waitcnt vmcnt(8)
	s_waitcnt lgkmcnt(0)
	s_barrier
	s_setprio 1
	s_waitcnt lgkmcnt(0)
	v_mfma_f32_16x16x32_bf16 v[70:73], v[58:61], v[198:201], v[70:73]
	v_mfma_f32_16x16x32_bf16 v[66:69], v[156:159], v[198:201], v[66:69]
	v_mfma_f32_16x16x32_bf16 v[46:49], v[58:61], v[206:209], v[46:49]
	v_mfma_f32_16x16x32_bf16 v[42:45], v[156:159], v[206:209], v[42:45]
	v_mfma_f32_16x16x32_bf16 v[30:33], v[58:61], v[236:239], v[30:33]
	v_mfma_f32_16x16x32_bf16 v[26:29], v[156:159], v[236:239], v[26:29]
	v_mfma_f32_16x16x32_bf16 v[14:17], v[58:61], v[244:247], v[14:17]
	v_mfma_f32_16x16x32_bf16 v[10:13], v[156:159], v[244:247], v[10:13]
	v_mfma_f32_16x16x32_bf16 v[70:73], v[62:65], v[202:205], v[70:73]
	v_mfma_f32_16x16x32_bf16 v[66:69], v[160:163], v[202:205], v[66:69]
	v_mfma_f32_16x16x32_bf16 v[46:49], v[62:65], v[232:235], v[46:49]
	v_mfma_f32_16x16x32_bf16 v[42:45], v[160:163], v[232:235], v[42:45]
	v_mfma_f32_16x16x32_bf16 v[30:33], v[62:65], v[240:243], v[30:33]
	v_mfma_f32_16x16x32_bf16 v[26:29], v[160:163], v[240:243], v[26:29]
	v_mfma_f32_16x16x32_bf16 v[14:17], v[62:65], v[248:251], v[14:17]
	v_mfma_f32_16x16x32_bf16 v[10:13], v[160:163], v[248:251], v[10:13]
	v_mfma_f32_16x16x32_bf16 v[50:53], v[164:167], v[198:201], v[50:53]
	v_mfma_f32_16x16x32_bf16 v[62:65], v[168:171], v[202:205], v[50:53]
	v_mfma_f32_16x16x32_bf16 v[50:53], v[190:193], v[198:201], v[54:57]
	v_mfma_f32_16x16x32_bf16 v[38:41], v[164:167], v[206:209], v[38:41]
	v_mfma_f32_16x16x32_bf16 v[34:37], v[190:193], v[206:209], v[34:37]
	v_mfma_f32_16x16x32_bf16 v[22:25], v[164:167], v[236:239], v[22:25]
	v_mfma_f32_16x16x32_bf16 v[18:21], v[190:193], v[236:239], v[18:21]
	v_mfma_f32_16x16x32_bf16 v[6:9], v[164:167], v[244:247], v[6:9]
	v_mfma_f32_16x16x32_bf16 v[2:5], v[190:193], v[244:247], v[2:5]
	v_mfma_f32_16x16x32_bf16 v[58:61], v[194:197], v[202:205], v[50:53]
	v_mfma_f32_16x16x32_bf16 v[38:41], v[168:171], v[232:235], v[38:41]
	v_mfma_f32_16x16x32_bf16 v[34:37], v[194:197], v[232:235], v[34:37]
	v_mfma_f32_16x16x32_bf16 v[22:25], v[168:171], v[240:243], v[22:25]
	v_mfma_f32_16x16x32_bf16 v[18:21], v[194:197], v[240:243], v[18:21]
	v_mfma_f32_16x16x32_bf16 v[6:9], v[168:171], v[248:251], v[6:9]
	v_mfma_f32_16x16x32_bf16 v[2:5], v[194:197], v[248:251], v[2:5]
	s_setprio 0
	s_barrier
	s_add_i32 s49, s49, 2
	s_add_u32 s4, s4, 0x100
	s_addc_u32 s5, s5, 0
	s_add_u32 s45, s45, 0x100
	s_addc_u32 s48, s48, 0
	s_cmp_gt_u32 s49, 29
	s_cbranch_scc0 .LBB0_288
	s_and_b64 vcc, exec, s[36:37]
	s_cbranch_vccz .LBB0_291
	s_barrier

.LBB0_1137:
	s_add_u32 s1, s54, s56
	s_addc_u32 s2, s55, s57
	s_add_u32 s1, s1, 0x100
	s_addc_u32 s2, s2, 0
	s_add_u32 s7, s70, s56
	s_addc_u32 s3, s71, s57
	s_add_i32 s8, 0, 0x10000
	s_cmpk_eq_i32 s56, 0x1300
	s_cselect_b32 s5, s43, s2
	s_cselect_b32 s4, s42, s1
	v_add_u32_e32 v0, s8, v153
	s_cselect_b32 s3, s53, s3
	s_cselect_b32 s2, s52, s7
	s_add_i32 s1, 0, 0x14000
	ds_read_b128 v[144:147], v0
	ds_read_b128 v[156:159], v0 offset:1024
	ds_read_b128 v[160:163], v0 offset:2048
	ds_read_b128 v[164:167], v0 offset:3072
	v_add_u32_e32 v0, s1, v153
	ds_read_b128 v[168:171], v0
	ds_read_b128 v[172:175], v0 offset:1024
	ds_read_b128 v[176:179], v0 offset:2048
	ds_read_b128 v[180:183], v0 offset:3072
	v_lshl_add_u64 v[2:3], v[140:141], 0, s[56:57]
	s_add_i32 m0, s37, 0xc000
	ds_read_b128 v[184:187], v155
	ds_read_b128 v[188:191], v155 offset:1024
	ds_read_b128 v[192:195], v155 offset:2048
	ds_read_b128 v[196:199], v155 offset:3072
	ds_read_b128 v[200:203], v155 offset:4096
	ds_read_b128 v[204:207], v155 offset:5120
	ds_read_b128 v[218:221], v155 offset:6144
	ds_read_b128 v[222:225], v155 offset:7168
	global_load_lds_dwordx4 v[2:3], off
	v_lshl_add_u64 v[2:3], v[142:143], 0, s[56:57]
	s_add_i32 m0, s37, 0xe000
	s_nop 0
	global_load_lds_dwordx4 v[2:3], off
	s_waitcnt vmcnt(8)
	s_waitcnt lgkmcnt(0)
	s_barrier
	s_setprio 1
	s_waitcnt lgkmcnt(0)
	v_mfma_f32_16x16x32_bf16 v[128:131], v[144:147], v[184:187], v[128:131]
	v_mfma_f32_16x16x32_bf16 v[124:127], v[160:163], v[184:187], v[124:127]
	v_mfma_f32_16x16x32_bf16 v[112:115], v[144:147], v[192:195], v[112:115]
	v_mfma_f32_16x16x32_bf16 v[108:111], v[160:163], v[192:195], v[108:111]
	v_mfma_f32_16x16x32_bf16 v[96:99], v[144:147], v[200:203], v[96:99]
	v_mfma_f32_16x16x32_bf16 v[92:95], v[160:163], v[200:203], v[92:95]
	v_mfma_f32_16x16x32_bf16 v[80:83], v[144:147], v[218:221], v[80:83]
	v_mfma_f32_16x16x32_bf16 v[76:79], v[160:163], v[218:221], v[76:79]
	v_mfma_f32_16x16x32_bf16 v[128:131], v[156:159], v[188:191], v[128:131]
	v_mfma_f32_16x16x32_bf16 v[124:127], v[164:167], v[188:191], v[124:127]
	v_mfma_f32_16x16x32_bf16 v[112:115], v[156:159], v[196:199], v[112:115]
	v_mfma_f32_16x16x32_bf16 v[108:111], v[164:167], v[196:199], v[108:111]
	v_mfma_f32_16x16x32_bf16 v[96:99], v[156:159], v[204:207], v[96:99]
	v_mfma_f32_16x16x32_bf16 v[92:95], v[164:167], v[204:207], v[92:95]
	v_mfma_f32_16x16x32_bf16 v[80:83], v[156:159], v[222:225], v[80:83]
	v_mfma_f32_16x16x32_bf16 v[76:79], v[164:167], v[222:225], v[76:79]
	v_mfma_f32_16x16x32_bf16 v[120:123], v[168:171], v[184:187], v[120:123]
	v_mfma_f32_16x16x32_bf16 v[116:119], v[176:179], v[184:187], v[116:119]
	v_mfma_f32_16x16x32_bf16 v[104:107], v[168:171], v[192:195], v[104:107]
	v_mfma_f32_16x16x32_bf16 v[100:103], v[176:179], v[192:195], v[100:103]
	v_mfma_f32_16x16x32_bf16 v[88:91], v[168:171], v[200:203], v[88:91]
	v_mfma_f32_16x16x32_bf16 v[84:87], v[176:179], v[200:203], v[84:87]
	v_mfma_f32_16x16x32_bf16 v[72:75], v[168:171], v[218:221], v[72:75]
	v_mfma_f32_16x16x32_bf16 v[68:71], v[176:179], v[218:221], v[68:71]
	v_mfma_f32_16x16x32_bf16 v[120:123], v[172:175], v[188:191], v[120:123]
	v_mfma_f32_16x16x32_bf16 v[116:119], v[180:183], v[188:191], v[116:119]
	v_mfma_f32_16x16x32_bf16 v[104:107], v[172:175], v[196:199], v[104:107]
	v_mfma_f32_16x16x32_bf16 v[100:103], v[180:183], v[196:199], v[100:103]
	v_mfma_f32_16x16x32_bf16 v[88:91], v[172:175], v[204:207], v[88:91]
	v_mfma_f32_16x16x32_bf16 v[84:87], v[180:183], v[204:207], v[84:87]
	v_mfma_f32_16x16x32_bf16 v[72:75], v[172:175], v[222:225], v[72:75]
	v_mfma_f32_16x16x32_bf16 v[68:71], v[180:183], v[222:225], v[68:71]
	s_setprio 0
	s_barrier
	s_add_i32 s7, s8, s36
	v_lshl_add_u64 v[148:149], s[2:3], 0, v[132:133]
	s_mov_b32 m0, s7
	ds_read_b128 v[184:187], v155 offset:16384
	ds_read_b128 v[188:191], v155 offset:17408
	ds_read_b128 v[192:195], v155 offset:18432
	ds_read_b128 v[196:199], v155 offset:19456
	ds_read_b128 v[200:203], v155 offset:20480
	ds_read_b128 v[204:207], v155 offset:21504
	ds_read_b128 v[218:221], v155 offset:22528
	ds_read_b128 v[222:225], v155 offset:23552
	global_load_lds_dwordx4 v[148:149], off
	s_add_i32 m0, s7, 0x2000
	s_add_u32 s8, s2, 0xa0000
	v_lshl_add_u64 v[208:209], s[2:3], 0, v[134:135]
	s_addc_u32 s9, s3, 0
	s_add_i32 s1, s1, s36
	global_load_lds_dwordx4 v[208:209], off
	v_lshl_add_u64 v[2:3], s[8:9], 0, v[132:133]
	s_mov_b32 m0, s1
	v_lshl_add_u64 v[232:233], s[4:5], 0, v[132:133]
	global_load_lds_dwordx4 v[2:3], off
	v_lshl_add_u64 v[2:3], s[8:9], 0, v[134:135]
	s_add_i32 m0, s1, 0x2000
	v_lshl_add_u64 v[234:235], s[4:5], 0, v[134:135]
	global_load_lds_dwordx4 v[2:3], off
	s_mov_b32 m0, s37
	s_nop 0
	global_load_lds_dwordx4 v[232:233], off
	s_mov_b32 m0, s38
	s_nop 0
	global_load_lds_dwordx4 v[234:235], off
	s_waitcnt vmcnt(8)
	s_waitcnt lgkmcnt(0)
	s_barrier
	s_setprio 1
	s_waitcnt lgkmcnt(0)
	v_mfma_f32_16x16x32_bf16 v[64:67], v[144:147], v[184:187], v[64:67]
	v_mfma_f32_16x16x32_bf16 v[60:63], v[160:163], v[184:187], v[60:63]
	v_mfma_f32_16x16x32_bf16 v[48:51], v[144:147], v[192:195], v[48:51]
	v_mfma_f32_16x16x32_bf16 v[44:47], v[160:163], v[192:195], v[44:47]
	v_mfma_f32_16x16x32_bf16 v[32:35], v[144:147], v[200:203], v[32:35]
	v_mfma_f32_16x16x32_bf16 v[28:31], v[160:163], v[200:203], v[28:31]
	v_mfma_f32_16x16x32_bf16 v[16:19], v[144:147], v[218:221], v[16:19]
	v_mfma_f32_16x16x32_bf16 v[12:15], v[160:163], v[218:221], v[12:15]
	v_mfma_f32_16x16x32_bf16 v[64:67], v[156:159], v[188:191], v[64:67]
	v_mfma_f32_16x16x32_bf16 v[60:63], v[164:167], v[188:191], v[60:63]
	v_mfma_f32_16x16x32_bf16 v[48:51], v[156:159], v[196:199], v[48:51]
	v_mfma_f32_16x16x32_bf16 v[44:47], v[164:167], v[196:199], v[44:47]
	v_mfma_f32_16x16x32_bf16 v[32:35], v[156:159], v[204:207], v[32:35]
	v_mfma_f32_16x16x32_bf16 v[28:31], v[164:167], v[204:207], v[28:31]
	v_mfma_f32_16x16x32_bf16 v[16:19], v[156:159], v[222:225], v[16:19]
	v_mfma_f32_16x16x32_bf16 v[12:15], v[164:167], v[222:225], v[12:15]
	v_mfma_f32_16x16x32_bf16 v[56:59], v[168:171], v[184:187], v[56:59]
	v_mfma_f32_16x16x32_bf16 v[52:55], v[176:179], v[184:187], v[52:55]
	v_mfma_f32_16x16x32_bf16 v[40:43], v[168:171], v[192:195], v[40:43]
	v_mfma_f32_16x16x32_bf16 v[36:39], v[176:179], v[192:195], v[36:39]
	v_mfma_f32_16x16x32_bf16 v[24:27], v[168:171], v[200:203], v[24:27]
	v_mfma_f32_16x16x32_bf16 v[20:23], v[176:179], v[200:203], v[20:23]
	v_mfma_f32_16x16x32_bf16 v[8:11], v[168:171], v[218:221], v[8:11]
	v_mfma_f32_16x16x32_bf16 v[2:5], v[176:179], v[218:221], v[4:7]
	v_mfma_f32_16x16x32_bf16 v[56:59], v[172:175], v[188:191], v[56:59]
	v_mfma_f32_16x16x32_bf16 v[52:55], v[180:183], v[188:191], v[52:55]
	v_mfma_f32_16x16x32_bf16 v[40:43], v[172:175], v[196:199], v[40:43]
	v_mfma_f32_16x16x32_bf16 v[36:39], v[180:183], v[196:199], v[36:39]
	v_mfma_f32_16x16x32_bf16 v[24:27], v[172:175], v[204:207], v[24:27]
	v_mfma_f32_16x16x32_bf16 v[20:23], v[180:183], v[204:207], v[20:23]
	v_mfma_f32_16x16x32_bf16 v[8:11], v[172:175], v[222:225], v[8:11]
	v_mfma_f32_16x16x32_bf16 v[2:5], v[180:183], v[222:225], v[2:5]
	s_setprio 0
	s_barrier
	s_add_i32 s1, 0, 0x18000
	v_add_u32_e32 v0, s1, v153
	s_add_i32 s7, 0, 0x1c000
	ds_read_b128 v[144:147], v0
	ds_read_b128 v[156:159], v0 offset:1024
	ds_read_b128 v[160:163], v0 offset:2048
	ds_read_b128 v[164:167], v0 offset:3072
	v_add_u32_e32 v0, s7, v153
	ds_read_b128 v[168:171], v0
	ds_read_b128 v[172:175], v0 offset:1024
	ds_read_b128 v[176:179], v0 offset:2048
	ds_read_b128 v[180:183], v0 offset:3072
	s_add_u32 s4, s4, 0xa0000
	s_addc_u32 s5, s5, 0
	s_mov_b32 m0, s39
	v_lshl_add_u64 v[6:7], s[4:5], 0, v[132:133]
	ds_read_b128 v[184:187], v155 offset:32768
	ds_read_b128 v[188:191], v155 offset:33792
	ds_read_b128 v[192:195], v155 offset:34816
	ds_read_b128 v[196:199], v155 offset:35840
	ds_read_b128 v[200:203], v155 offset:36864
	ds_read_b128 v[204:207], v155 offset:37888
	ds_read_b128 v[218:221], v155 offset:38912
	ds_read_b128 v[222:225], v155 offset:39936
	global_load_lds_dwordx4 v[6:7], off
	v_lshl_add_u64 v[6:7], s[4:5], 0, v[134:135]
	s_mov_b32 m0, s58
	s_nop 0
	global_load_lds_dwordx4 v[6:7], off
	s_waitcnt vmcnt(8)
	s_waitcnt lgkmcnt(0)
	s_barrier
	s_setprio 1
	s_waitcnt lgkmcnt(0)
	v_mfma_f32_16x16x32_bf16 v[128:131], v[144:147], v[184:187], v[128:131]
	v_mfma_f32_16x16x32_bf16 v[124:127], v[160:163], v[184:187], v[124:127]
	v_mfma_f32_16x16x32_bf16 v[112:115], v[144:147], v[192:195], v[112:115]
	v_mfma_f32_16x16x32_bf16 v[108:111], v[160:163], v[192:195], v[108:111]
	v_mfma_f32_16x16x32_bf16 v[96:99], v[144:147], v[200:203], v[96:99]
	v_mfma_f32_16x16x32_bf16 v[92:95], v[160:163], v[200:203], v[92:95]
	v_mfma_f32_16x16x32_bf16 v[80:83], v[144:147], v[218:221], v[80:83]
	v_mfma_f32_16x16x32_bf16 v[76:79], v[160:163], v[218:221], v[76:79]
	v_mfma_f32_16x16x32_bf16 v[128:131], v[156:159], v[188:191], v[128:131]
	v_mfma_f32_16x16x32_bf16 v[124:127], v[164:167], v[188:191], v[124:127]
	v_mfma_f32_16x16x32_bf16 v[112:115], v[156:159], v[196:199], v[112:115]
	v_mfma_f32_16x16x32_bf16 v[108:111], v[164:167], v[196:199], v[108:111]
	v_mfma_f32_16x16x32_bf16 v[96:99], v[156:159], v[204:207], v[96:99]
	v_mfma_f32_16x16x32_bf16 v[92:95], v[164:167], v[204:207], v[92:95]
	v_mfma_f32_16x16x32_bf16 v[80:83], v[156:159], v[222:225], v[80:83]
	v_mfma_f32_16x16x32_bf16 v[76:79], v[164:167], v[222:225], v[76:79]
	v_mfma_f32_16x16x32_bf16 v[120:123], v[168:171], v[184:187], v[120:123]
	v_mfma_f32_16x16x32_bf16 v[116:119], v[176:179], v[184:187], v[116:119]
	v_mfma_f32_16x16x32_bf16 v[104:107], v[168:171], v[192:195], v[104:107]
	v_mfma_f32_16x16x32_bf16 v[100:103], v[176:179], v[192:195], v[100:103]
	v_mfma_f32_16x16x32_bf16 v[88:91], v[168:171], v[200:203], v[88:91]
	v_mfma_f32_16x16x32_bf16 v[84:87], v[176:179], v[200:203], v[84:87]
	v_mfma_f32_16x16x32_bf16 v[72:75], v[168:171], v[218:221], v[72:75]
	v_mfma_f32_16x16x32_bf16 v[68:71], v[176:179], v[218:221], v[68:71]
	v_mfma_f32_16x16x32_bf16 v[120:123], v[172:175], v[188:191], v[120:123]
	v_mfma_f32_16x16x32_bf16 v[116:119], v[180:183], v[188:191], v[116:119]
	v_mfma_f32_16x16x32_bf16 v[104:107], v[172:175], v[196:199], v[104:107]
	v_mfma_f32_16x16x32_bf16 v[100:103], v[180:183], v[196:199], v[100:103]
	v_mfma_f32_16x16x32_bf16 v[88:91], v[172:175], v[204:207], v[88:91]
	v_mfma_f32_16x16x32_bf16 v[84:87], v[180:183], v[204:207], v[84:87]
	v_mfma_f32_16x16x32_bf16 v[72:75], v[172:175], v[222:225], v[72:75]
	v_mfma_f32_16x16x32_bf16 v[68:71], v[180:183], v[222:225], v[68:71]
	s_setprio 0
	s_barrier
	s_add_i32 s1, s1, s36
	v_lshl_add_u64 v[6:7], v[148:149], 0, s[16:17]
	s_mov_b32 m0, s1
	ds_read_b128 v[184:187], v155 offset:49152
	ds_read_b128 v[188:191], v155 offset:50176
	ds_read_b128 v[192:195], v155 offset:51200
	ds_read_b128 v[196:199], v155 offset:52224
	ds_read_b128 v[200:203], v155 offset:53248
	ds_read_b128 v[204:207], v155 offset:54272
	ds_read_b128 v[218:221], v155 offset:55296
	ds_read_b128 v[222:225], v155 offset:56320
	global_load_lds_dwordx4 v[6:7], off
	s_add_i32 m0, s1, 0x2000
	s_add_u32 s2, s2, 0xa0080
	v_lshl_add_u64 v[6:7], v[208:209], 0, s[16:17]
	s_addc_u32 s3, s3, 0
	s_add_i32 s1, s7, s36
	global_load_lds_dwordx4 v[6:7], off
	v_lshl_add_u64 v[6:7], s[2:3], 0, v[132:133]
	s_mov_b32 m0, s1
	s_nop 0
	global_load_lds_dwordx4 v[6:7], off
	v_lshl_add_u64 v[6:7], s[2:3], 0, v[134:135]
	s_add_i32 m0, s1, 0x2000
	s_nop 0
	global_load_lds_dwordx4 v[6:7], off
	v_lshl_add_u64 v[6:7], v[232:233], 0, s[16:17]
	s_mov_b32 m0, s61
	s_nop 0
	global_load_lds_dwordx4 v[6:7], off
	v_lshl_add_u64 v[6:7], v[234:235], 0, s[16:17]
	s_mov_b32 m0, s62
	s_nop 0
	global_load_lds_dwordx4 v[6:7], off
	s_waitcnt vmcnt(8)
	s_waitcnt lgkmcnt(0)
	s_barrier
	s_setprio 1
	s_waitcnt lgkmcnt(0)
	v_mfma_f32_16x16x32_bf16 v[64:67], v[144:147], v[184:187], v[64:67]
	v_mfma_f32_16x16x32_bf16 v[60:63], v[160:163], v[184:187], v[60:63]
	v_mfma_f32_16x16x32_bf16 v[48:51], v[144:147], v[192:195], v[48:51]
	v_mfma_f32_16x16x32_bf16 v[44:47], v[160:163], v[192:195], v[44:47]
	v_mfma_f32_16x16x32_bf16 v[32:35], v[144:147], v[200:203], v[32:35]
	v_mfma_f32_16x16x32_bf16 v[28:31], v[160:163], v[200:203], v[28:31]
	v_mfma_f32_16x16x32_bf16 v[16:19], v[144:147], v[218:221], v[16:19]
	v_mfma_f32_16x16x32_bf16 v[12:15], v[160:163], v[218:221], v[12:15]
	v_mfma_f32_16x16x32_bf16 v[64:67], v[156:159], v[188:191], v[64:67]
	v_mfma_f32_16x16x32_bf16 v[60:63], v[164:167], v[188:191], v[60:63]
	v_mfma_f32_16x16x32_bf16 v[48:51], v[156:159], v[196:199], v[48:51]
	v_mfma_f32_16x16x32_bf16 v[44:47], v[164:167], v[196:199], v[44:47]
	v_mfma_f32_16x16x32_bf16 v[32:35], v[156:159], v[204:207], v[32:35]
	v_mfma_f32_16x16x32_bf16 v[28:31], v[164:167], v[204:207], v[28:31]
	v_mfma_f32_16x16x32_bf16 v[16:19], v[156:159], v[222:225], v[16:19]
	v_mfma_f32_16x16x32_bf16 v[12:15], v[164:167], v[222:225], v[12:15]
	v_mfma_f32_16x16x32_bf16 v[56:59], v[168:171], v[184:187], v[56:59]
	v_mfma_f32_16x16x32_bf16 v[52:55], v[176:179], v[184:187], v[52:55]
	v_mfma_f32_16x16x32_bf16 v[40:43], v[168:171], v[192:195], v[40:43]
	v_mfma_f32_16x16x32_bf16 v[36:39], v[176:179], v[192:195], v[36:39]
	v_mfma_f32_16x16x32_bf16 v[24:27], v[168:171], v[200:203], v[24:27]
	v_mfma_f32_16x16x32_bf16 v[20:23], v[176:179], v[200:203], v[20:23]
	v_mfma_f32_16x16x32_bf16 v[6:9], v[168:171], v[218:221], v[8:11]
	v_mfma_f32_16x16x32_bf16 v[2:5], v[176:179], v[218:221], v[2:5]
	v_mfma_f32_16x16x32_bf16 v[56:59], v[172:175], v[188:191], v[56:59]
	v_mfma_f32_16x16x32_bf16 v[52:55], v[180:183], v[188:191], v[52:55]
	v_mfma_f32_16x16x32_bf16 v[40:43], v[172:175], v[196:199], v[40:43]
	v_mfma_f32_16x16x32_bf16 v[36:39], v[180:183], v[196:199], v[36:39]
	v_mfma_f32_16x16x32_bf16 v[24:27], v[172:175], v[204:207], v[24:27]
	v_mfma_f32_16x16x32_bf16 v[20:23], v[180:183], v[204:207], v[20:23]
	v_mfma_f32_16x16x32_bf16 v[8:11], v[172:175], v[222:225], v[6:9]
	v_mfma_f32_16x16x32_bf16 v[4:7], v[180:183], v[222:225], v[2:5]
	s_setprio 0
	s_barrier
	s_add_i32 s1, s76, 2
	s_add_u32 s56, s56, 0x100
	s_addc_u32 s57, s57, 0
	s_cmp_gt_u32 s76, 37
	s_cbranch_scc1 .LBB0_1139
	s_mov_b32 s76, s1
	s_and_b32 s1, s76, 54
	s_cmp_eq_u32 s1, 16
	s_mov_b64 s[2:3], -1
	s_cbranch_scc0 .LBB0_1134
	s_branch .LBB0_1135

.LBB0_1227:
	s_add_u32 s38, s4, 0x100
	s_addc_u32 s39, s5, 0
	s_add_i32 s12, 0, 0x10000
	s_cmp_eq_u32 s57, 28
	s_cselect_b32 s63, s10, s39
	s_cselect_b32 s62, s28, s38
	s_cselect_b32 s61, s29, s51
	s_cselect_b32 s60, s35, s49
	s_add_i32 s59, 0, 0x14000
	v_add_u32_e32 v138, s12, v232
	v_add_u32_e32 v158, s59, v232
	ds_read_b128 v[126:129], v138
	ds_read_b128 v[130:133], v138 offset:1024
	ds_read_b128 v[134:137], v138 offset:2048
	ds_read_b128 v[138:141], v138 offset:3072
	ds_read_b128 v[146:149], v158
	ds_read_b128 v[150:153], v158 offset:1024
	ds_read_b128 v[154:157], v158 offset:2048
	ds_read_b128 v[158:161], v158 offset:3072
	v_lshl_add_u64 v[200:201], s[4:5], 0, v[192:193]
	s_add_i32 m0, s15, 0xc000
	ds_read_b128 v[162:165], v234
	ds_read_b128 v[166:169], v234 offset:1024
	ds_read_b128 v[170:173], v234 offset:2048
	ds_read_b128 v[174:177], v234 offset:3072
	ds_read_b128 v[178:181], v234 offset:4096
	ds_read_b128 v[182:185], v234 offset:5120
	ds_read_b128 v[186:189], v234 offset:6144
	ds_read_b128 v[196:199], v234 offset:7168
	global_load_lds_dwordx4 v[200:201], off
	v_lshl_add_u64 v[200:201], s[4:5], 0, v[194:195]
	s_add_i32 m0, s15, 0xe000
	s_nop 0
	global_load_lds_dwordx4 v[200:201], off
	s_waitcnt vmcnt(8)
	s_waitcnt lgkmcnt(0)
	s_barrier
	s_setprio 1
	s_waitcnt lgkmcnt(0)
	v_mfma_f32_16x16x32_bf16 v[142:145], v[126:129], v[162:165], v[142:145]
	v_mfma_f32_16x16x32_bf16 v[122:125], v[134:137], v[162:165], v[122:125]
	v_mfma_f32_16x16x32_bf16 v[110:113], v[126:129], v[170:173], v[110:113]
	v_mfma_f32_16x16x32_bf16 v[106:109], v[134:137], v[170:173], v[106:109]
	v_mfma_f32_16x16x32_bf16 v[94:97], v[126:129], v[178:181], v[94:97]
	v_mfma_f32_16x16x32_bf16 v[90:93], v[134:137], v[178:181], v[90:93]
	v_mfma_f32_16x16x32_bf16 v[78:81], v[126:129], v[186:189], v[78:81]
	v_mfma_f32_16x16x32_bf16 v[74:77], v[134:137], v[186:189], v[74:77]
	v_mfma_f32_16x16x32_bf16 v[142:145], v[130:133], v[166:169], v[142:145]
	v_mfma_f32_16x16x32_bf16 v[122:125], v[138:141], v[166:169], v[122:125]
	v_mfma_f32_16x16x32_bf16 v[110:113], v[130:133], v[174:177], v[110:113]
	v_mfma_f32_16x16x32_bf16 v[106:109], v[138:141], v[174:177], v[106:109]
	v_mfma_f32_16x16x32_bf16 v[94:97], v[130:133], v[182:185], v[94:97]
	v_mfma_f32_16x16x32_bf16 v[90:93], v[138:141], v[182:185], v[90:93]
	v_mfma_f32_16x16x32_bf16 v[78:81], v[130:133], v[196:199], v[78:81]
	v_mfma_f32_16x16x32_bf16 v[74:77], v[138:141], v[196:199], v[74:77]
	v_mfma_f32_16x16x32_bf16 v[118:121], v[146:149], v[162:165], v[118:121]
	v_mfma_f32_16x16x32_bf16 v[114:117], v[154:157], v[162:165], v[114:117]
	v_mfma_f32_16x16x32_bf16 v[102:105], v[146:149], v[170:173], v[102:105]
	v_mfma_f32_16x16x32_bf16 v[98:101], v[154:157], v[170:173], v[98:101]
	v_mfma_f32_16x16x32_bf16 v[86:89], v[146:149], v[178:181], v[86:89]
	v_mfma_f32_16x16x32_bf16 v[82:85], v[154:157], v[178:181], v[82:85]
	v_mfma_f32_16x16x32_bf16 v[70:73], v[146:149], v[186:189], v[70:73]
	v_mfma_f32_16x16x32_bf16 v[66:69], v[154:157], v[186:189], v[66:69]
	v_mfma_f32_16x16x32_bf16 v[118:121], v[150:153], v[166:169], v[118:121]
	v_mfma_f32_16x16x32_bf16 v[114:117], v[158:161], v[166:169], v[114:117]
	v_mfma_f32_16x16x32_bf16 v[102:105], v[150:153], v[174:177], v[102:105]
	v_mfma_f32_16x16x32_bf16 v[98:101], v[158:161], v[174:177], v[98:101]
	v_mfma_f32_16x16x32_bf16 v[86:89], v[150:153], v[182:185], v[86:89]
	v_mfma_f32_16x16x32_bf16 v[82:85], v[158:161], v[182:185], v[82:85]
	v_mfma_f32_16x16x32_bf16 v[70:73], v[150:153], v[196:199], v[70:73]
	v_mfma_f32_16x16x32_bf16 v[66:69], v[158:161], v[196:199], v[66:69]
	s_setprio 0
	s_barrier
	s_add_i32 s4, s12, s14
	v_lshl_add_u64 v[200:201], s[60:61], 0, v[0:1]
	s_mov_b32 m0, s4
	ds_read_b128 v[162:165], v234 offset:16384
	ds_read_b128 v[166:169], v234 offset:17408
	ds_read_b128 v[170:173], v234 offset:18432
	ds_read_b128 v[174:177], v234 offset:19456
	ds_read_b128 v[178:181], v234 offset:20480
	ds_read_b128 v[182:185], v234 offset:21504
	ds_read_b128 v[186:189], v234 offset:22528
	ds_read_b128 v[196:199], v234 offset:23552
	global_load_lds_dwordx4 v[200:201], off
	s_add_i32 m0, s4, 0x2000
	s_add_u32 s4, s60, 0x80000
	v_lshl_add_u64 v[202:203], s[60:61], 0, v[190:191]
	s_addc_u32 s5, s61, 0
	s_add_i32 s12, s59, s14
	global_load_lds_dwordx4 v[202:203], off
	v_lshl_add_u64 v[204:205], s[4:5], 0, v[0:1]
	s_mov_b32 m0, s12
	v_lshl_add_u64 v[206:207], s[62:63], 0, v[190:191]
	global_load_lds_dwordx4 v[204:205], off
	v_lshl_add_u64 v[204:205], s[4:5], 0, v[190:191]
	s_add_i32 m0, s12, 0x2000
	s_nop 0
	global_load_lds_dwordx4 v[204:205], off
	v_lshl_add_u64 v[204:205], s[62:63], 0, v[0:1]
	s_mov_b32 m0, s15
	s_nop 0
	global_load_lds_dwordx4 v[204:205], off
	s_mov_b32 m0, s20
	s_nop 0
	global_load_lds_dwordx4 v[206:207], off
	s_waitcnt vmcnt(8)
	s_waitcnt lgkmcnt(0)
	s_barrier
	s_setprio 1
	s_waitcnt lgkmcnt(0)
	v_mfma_f32_16x16x32_bf16 v[62:65], v[126:129], v[162:165], v[62:65]
	v_mfma_f32_16x16x32_bf16 v[58:61], v[134:137], v[162:165], v[58:61]
	v_mfma_f32_16x16x32_bf16 v[46:49], v[126:129], v[170:173], v[46:49]
	v_mfma_f32_16x16x32_bf16 v[42:45], v[134:137], v[170:173], v[42:45]
	v_mfma_f32_16x16x32_bf16 v[30:33], v[126:129], v[178:181], v[30:33]
	v_mfma_f32_16x16x32_bf16 v[26:29], v[134:137], v[178:181], v[26:29]
	v_mfma_f32_16x16x32_bf16 v[14:17], v[126:129], v[186:189], v[14:17]
	v_mfma_f32_16x16x32_bf16 v[10:13], v[134:137], v[186:189], v[10:13]
	v_mfma_f32_16x16x32_bf16 v[62:65], v[130:133], v[166:169], v[62:65]
	v_mfma_f32_16x16x32_bf16 v[58:61], v[138:141], v[166:169], v[58:61]
	v_mfma_f32_16x16x32_bf16 v[46:49], v[130:133], v[174:177], v[46:49]
	v_mfma_f32_16x16x32_bf16 v[42:45], v[138:141], v[174:177], v[42:45]
	v_mfma_f32_16x16x32_bf16 v[30:33], v[130:133], v[182:185], v[30:33]
	v_mfma_f32_16x16x32_bf16 v[26:29], v[138:141], v[182:185], v[26:29]
	v_mfma_f32_16x16x32_bf16 v[14:17], v[130:133], v[196:199], v[14:17]
	v_mfma_f32_16x16x32_bf16 v[10:13], v[138:141], v[196:199], v[10:13]
	v_mfma_f32_16x16x32_bf16 v[54:57], v[146:149], v[162:165], v[54:57]
	v_mfma_f32_16x16x32_bf16 v[50:53], v[154:157], v[162:165], v[50:53]
	v_mfma_f32_16x16x32_bf16 v[38:41], v[146:149], v[170:173], v[38:41]
	v_mfma_f32_16x16x32_bf16 v[34:37], v[154:157], v[170:173], v[34:37]
	v_mfma_f32_16x16x32_bf16 v[22:25], v[146:149], v[178:181], v[22:25]
	v_mfma_f32_16x16x32_bf16 v[18:21], v[154:157], v[178:181], v[18:21]
	v_mfma_f32_16x16x32_bf16 v[6:9], v[146:149], v[186:189], v[6:9]
	v_mfma_f32_16x16x32_bf16 v[2:5], v[154:157], v[186:189], v[2:5]
	v_mfma_f32_16x16x32_bf16 v[54:57], v[150:153], v[166:169], v[54:57]
	v_mfma_f32_16x16x32_bf16 v[50:53], v[158:161], v[166:169], v[50:53]
	v_mfma_f32_16x16x32_bf16 v[38:41], v[150:153], v[174:177], v[38:41]
	v_mfma_f32_16x16x32_bf16 v[34:37], v[158:161], v[174:177], v[34:37]
	v_mfma_f32_16x16x32_bf16 v[22:25], v[150:153], v[182:185], v[22:25]
	v_mfma_f32_16x16x32_bf16 v[18:21], v[158:161], v[182:185], v[18:21]
	v_mfma_f32_16x16x32_bf16 v[6:9], v[150:153], v[196:199], v[6:9]
	v_mfma_f32_16x16x32_bf16 v[2:5], v[158:161], v[196:199], v[2:5]
	s_setprio 0
	s_barrier
	s_add_i32 s12, 0, 0x18000
	s_add_i32 s59, 0, 0x1c000
	v_add_u32_e32 v138, s12, v232
	v_add_u32_e32 v158, s59, v232
	ds_read_b128 v[126:129], v138
	ds_read_b128 v[130:133], v138 offset:1024
	ds_read_b128 v[134:137], v138 offset:2048
	ds_read_b128 v[138:141], v138 offset:3072
	ds_read_b128 v[146:149], v158
	ds_read_b128 v[150:153], v158 offset:1024
	ds_read_b128 v[154:157], v158 offset:2048
	ds_read_b128 v[158:161], v158 offset:3072
	s_add_u32 s4, s62, 0x80000
	s_addc_u32 s5, s63, 0
	s_mov_b32 m0, s21
	v_lshl_add_u64 v[208:209], s[4:5], 0, v[0:1]
	ds_read_b128 v[162:165], v234 offset:32768
	ds_read_b128 v[166:169], v234 offset:33792
	ds_read_b128 v[170:173], v234 offset:34816
	ds_read_b128 v[174:177], v234 offset:35840
	ds_read_b128 v[178:181], v234 offset:36864
	ds_read_b128 v[182:185], v234 offset:37888
	ds_read_b128 v[186:189], v234 offset:38912
	ds_read_b128 v[196:199], v234 offset:39936
	global_load_lds_dwordx4 v[208:209], off
	v_lshl_add_u64 v[208:209], s[4:5], 0, v[190:191]
	s_mov_b32 m0, s22
	s_nop 0
	global_load_lds_dwordx4 v[208:209], off
	s_waitcnt vmcnt(8)
	s_waitcnt lgkmcnt(0)
	s_barrier
	s_setprio 1
	s_waitcnt lgkmcnt(0)
	v_mfma_f32_16x16x32_bf16 v[142:145], v[126:129], v[162:165], v[142:145]
	v_mfma_f32_16x16x32_bf16 v[122:125], v[134:137], v[162:165], v[122:125]
	v_mfma_f32_16x16x32_bf16 v[110:113], v[126:129], v[170:173], v[110:113]
	v_mfma_f32_16x16x32_bf16 v[106:109], v[134:137], v[170:173], v[106:109]
	v_mfma_f32_16x16x32_bf16 v[94:97], v[126:129], v[178:181], v[94:97]
	v_mfma_f32_16x16x32_bf16 v[90:93], v[134:137], v[178:181], v[90:93]
	v_mfma_f32_16x16x32_bf16 v[78:81], v[126:129], v[186:189], v[78:81]
	v_mfma_f32_16x16x32_bf16 v[74:77], v[134:137], v[186:189], v[74:77]
	v_mfma_f32_16x16x32_bf16 v[142:145], v[130:133], v[166:169], v[142:145]
	v_mfma_f32_16x16x32_bf16 v[122:125], v[138:141], v[166:169], v[122:125]
	v_mfma_f32_16x16x32_bf16 v[110:113], v[130:133], v[174:177], v[110:113]
	v_mfma_f32_16x16x32_bf16 v[106:109], v[138:141], v[174:177], v[106:109]
	v_mfma_f32_16x16x32_bf16 v[94:97], v[130:133], v[182:185], v[94:97]
	v_mfma_f32_16x16x32_bf16 v[90:93], v[138:141], v[182:185], v[90:93]
	v_mfma_f32_16x16x32_bf16 v[78:81], v[130:133], v[196:199], v[78:81]
	v_mfma_f32_16x16x32_bf16 v[74:77], v[138:141], v[196:199], v[74:77]
	v_mfma_f32_16x16x32_bf16 v[118:121], v[146:149], v[162:165], v[118:121]
	v_mfma_f32_16x16x32_bf16 v[114:117], v[154:157], v[162:165], v[114:117]
	v_mfma_f32_16x16x32_bf16 v[102:105], v[146:149], v[170:173], v[102:105]
	v_mfma_f32_16x16x32_bf16 v[98:101], v[154:157], v[170:173], v[98:101]
	v_mfma_f32_16x16x32_bf16 v[86:89], v[146:149], v[178:181], v[86:89]
	v_mfma_f32_16x16x32_bf16 v[82:85], v[154:157], v[178:181], v[82:85]
	v_mfma_f32_16x16x32_bf16 v[70:73], v[146:149], v[186:189], v[70:73]
	v_mfma_f32_16x16x32_bf16 v[66:69], v[154:157], v[186:189], v[66:69]
	v_mfma_f32_16x16x32_bf16 v[118:121], v[150:153], v[166:169], v[118:121]
	v_mfma_f32_16x16x32_bf16 v[114:117], v[158:161], v[166:169], v[114:117]
	v_mfma_f32_16x16x32_bf16 v[102:105], v[150:153], v[174:177], v[102:105]
	v_mfma_f32_16x16x32_bf16 v[98:101], v[158:161], v[174:177], v[98:101]
	v_mfma_f32_16x16x32_bf16 v[86:89], v[150:153], v[182:185], v[86:89]
	v_mfma_f32_16x16x32_bf16 v[82:85], v[158:161], v[182:185], v[82:85]
	v_mfma_f32_16x16x32_bf16 v[70:73], v[150:153], v[196:199], v[70:73]
	v_mfma_f32_16x16x32_bf16 v[66:69], v[158:161], v[196:199], v[66:69]
	s_setprio 0
	s_barrier
	s_add_i32 s4, s12, s14
	v_lshl_add_u64 v[200:201], v[200:201], 0, s[16:17]
	s_mov_b32 m0, s4
	ds_read_b128 v[162:165], v234 offset:49152
	ds_read_b128 v[166:169], v234 offset:50176
	ds_read_b128 v[170:173], v234 offset:51200
	ds_read_b128 v[174:177], v234 offset:52224
	ds_read_b128 v[178:181], v234 offset:53248
	ds_read_b128 v[182:185], v234 offset:54272
	ds_read_b128 v[186:189], v234 offset:55296
	ds_read_b128 v[196:199], v234 offset:56320
	global_load_lds_dwordx4 v[200:201], off
	s_add_i32 m0, s4, 0x2000
	s_add_u32 s4, s60, 0x80080
	v_lshl_add_u64 v[200:201], v[202:203], 0, s[16:17]
	s_addc_u32 s5, s61, 0
	s_add_i32 s12, s59, s14
	global_load_lds_dwordx4 v[200:201], off
	v_lshl_add_u64 v[200:201], s[4:5], 0, v[0:1]
	s_mov_b32 m0, s12
	s_nop 0
	global_load_lds_dwordx4 v[200:201], off
	v_lshl_add_u64 v[200:201], s[4:5], 0, v[190:191]
	s_add_i32 m0, s12, 0x2000
	s_nop 0
	global_load_lds_dwordx4 v[200:201], off
	v_lshl_add_u64 v[200:201], v[204:205], 0, s[16:17]
	s_mov_b32 m0, s26
	s_nop 0
	global_load_lds_dwordx4 v[200:201], off
	v_lshl_add_u64 v[200:201], v[206:207], 0, s[16:17]
	s_mov_b32 m0, s27
	s_nop 0
	global_load_lds_dwordx4 v[200:201], off
	s_waitcnt vmcnt(8)
	s_waitcnt lgkmcnt(0)
	s_barrier
	s_setprio 1
	s_waitcnt lgkmcnt(0)
	v_mfma_f32_16x16x32_bf16 v[62:65], v[126:129], v[162:165], v[62:65]
	v_mfma_f32_16x16x32_bf16 v[58:61], v[134:137], v[162:165], v[58:61]
	v_mfma_f32_16x16x32_bf16 v[46:49], v[126:129], v[170:173], v[46:49]
	v_mfma_f32_16x16x32_bf16 v[42:45], v[134:137], v[170:173], v[42:45]
	v_mfma_f32_16x16x32_bf16 v[30:33], v[126:129], v[178:181], v[30:33]
	v_mfma_f32_16x16x32_bf16 v[26:29], v[134:137], v[178:181], v[26:29]
	v_mfma_f32_16x16x32_bf16 v[14:17], v[126:129], v[186:189], v[14:17]
	v_mfma_f32_16x16x32_bf16 v[10:13], v[134:137], v[186:189], v[10:13]
	v_mfma_f32_16x16x32_bf16 v[62:65], v[130:133], v[166:169], v[62:65]
	v_mfma_f32_16x16x32_bf16 v[58:61], v[138:141], v[166:169], v[58:61]
	v_mfma_f32_16x16x32_bf16 v[46:49], v[130:133], v[174:177], v[46:49]
	v_mfma_f32_16x16x32_bf16 v[42:45], v[138:141], v[174:177], v[42:45]
	v_mfma_f32_16x16x32_bf16 v[30:33], v[130:133], v[182:185], v[30:33]
	v_mfma_f32_16x16x32_bf16 v[26:29], v[138:141], v[182:185], v[26:29]
	v_mfma_f32_16x16x32_bf16 v[14:17], v[130:133], v[196:199], v[14:17]
	v_mfma_f32_16x16x32_bf16 v[10:13], v[138:141], v[196:199], v[10:13]
	v_mfma_f32_16x16x32_bf16 v[54:57], v[146:149], v[162:165], v[54:57]
	v_mfma_f32_16x16x32_bf16 v[50:53], v[154:157], v[162:165], v[50:53]
	v_mfma_f32_16x16x32_bf16 v[38:41], v[146:149], v[170:173], v[38:41]
	v_mfma_f32_16x16x32_bf16 v[34:37], v[154:157], v[170:173], v[34:37]
	v_mfma_f32_16x16x32_bf16 v[22:25], v[146:149], v[178:181], v[22:25]
	v_mfma_f32_16x16x32_bf16 v[18:21], v[154:157], v[178:181], v[18:21]
	v_mfma_f32_16x16x32_bf16 v[6:9], v[146:149], v[186:189], v[6:9]
	v_mfma_f32_16x16x32_bf16 v[2:5], v[154:157], v[186:189], v[2:5]
	v_mfma_f32_16x16x32_bf16 v[54:57], v[150:153], v[166:169], v[54:57]
	v_mfma_f32_16x16x32_bf16 v[50:53], v[158:161], v[166:169], v[50:53]
	v_mfma_f32_16x16x32_bf16 v[38:41], v[150:153], v[174:177], v[38:41]
	v_mfma_f32_16x16x32_bf16 v[34:37], v[158:161], v[174:177], v[34:37]
	v_mfma_f32_16x16x32_bf16 v[22:25], v[150:153], v[182:185], v[22:25]
	v_mfma_f32_16x16x32_bf16 v[18:21], v[158:161], v[182:185], v[18:21]
	v_mfma_f32_16x16x32_bf16 v[6:9], v[150:153], v[196:199], v[6:9]
	v_mfma_f32_16x16x32_bf16 v[2:5], v[158:161], v[196:199], v[2:5]
	s_setprio 0
	s_barrier
	s_add_i32 s57, s57, 2
	s_add_u32 s49, s49, 0x100
	s_addc_u32 s51, s51, 0
	s_cmp_gt_u32 s57, 29
	s_mov_b64 s[4:5], s[38:39]
	s_cbranch_scc0 .LBB0_1227
	s_and_b64 vcc, exec, s[46:47]
	s_cbranch_vccz .LBB0_1230
	s_barrier

.LBB0_1337:
	s_add_u32 s12, s4, 0xfff80080
	s_addc_u32 s38, s5, -1
	s_add_i32 s52, 0, 0x10000
	s_cmp_eq_u32 s49, 28
	s_cselect_b32 s51, s29, s38
	s_cselect_b32 s50, s33, s12
	v_add_u32_e32 v144, s52, v147
	s_cselect_b32 s39, s34, s43
	s_cselect_b32 s38, s35, s37
	s_add_i32 s12, 0, 0x14000
	ds_read_b128 v[140:143], v144
	ds_read_b128 v[152:155], v144 offset:1024
	ds_read_b128 v[156:159], v144 offset:2048
	ds_read_b128 v[160:163], v144 offset:3072
	v_add_u32_e32 v144, s12, v147
	ds_read_b128 v[164:167], v144
	ds_read_b128 v[168:171], v144 offset:1024
	ds_read_b128 v[172:175], v144 offset:2048
	ds_read_b128 v[176:179], v144 offset:3072
	v_lshl_add_u64 v[144:145], s[4:5], 0, v[136:137]
	s_add_i32 m0, s20, 0xc000
	ds_read_b128 v[180:183], v150
	ds_read_b128 v[184:187], v150 offset:1024
	ds_read_b128 v[188:191], v150 offset:2048
	ds_read_b128 v[192:195], v150 offset:3072
	ds_read_b128 v[196:199], v150 offset:4096
	ds_read_b128 v[200:203], v150 offset:5120
	ds_read_b128 v[204:207], v150 offset:6144
	ds_read_b128 v[218:221], v150 offset:7168
	global_load_lds_dwordx4 v[144:145], off
	v_lshl_add_u64 v[144:145], s[4:5], 0, v[138:139]
	s_add_i32 m0, s20, 0xe000
	s_nop 0
	global_load_lds_dwordx4 v[144:145], off
	s_waitcnt vmcnt(8)
	s_waitcnt lgkmcnt(0)
	s_barrier
	s_setprio 1
	s_waitcnt lgkmcnt(0)
	v_mfma_f32_16x16x32_bf16 v[126:129], v[140:143], v[180:183], v[126:129]
	v_mfma_f32_16x16x32_bf16 v[122:125], v[156:159], v[180:183], v[122:125]
	v_mfma_f32_16x16x32_bf16 v[110:113], v[140:143], v[188:191], v[110:113]
	v_mfma_f32_16x16x32_bf16 v[106:109], v[156:159], v[188:191], v[106:109]
	v_mfma_f32_16x16x32_bf16 v[94:97], v[140:143], v[196:199], v[94:97]
	v_mfma_f32_16x16x32_bf16 v[90:93], v[156:159], v[196:199], v[90:93]
	v_mfma_f32_16x16x32_bf16 v[78:81], v[140:143], v[204:207], v[78:81]
	v_mfma_f32_16x16x32_bf16 v[74:77], v[156:159], v[204:207], v[74:77]
	v_mfma_f32_16x16x32_bf16 v[126:129], v[152:155], v[184:187], v[126:129]
	v_mfma_f32_16x16x32_bf16 v[122:125], v[160:163], v[184:187], v[122:125]
	v_mfma_f32_16x16x32_bf16 v[110:113], v[152:155], v[192:195], v[110:113]
	v_mfma_f32_16x16x32_bf16 v[106:109], v[160:163], v[192:195], v[106:109]
	v_mfma_f32_16x16x32_bf16 v[94:97], v[152:155], v[200:203], v[94:97]
	v_mfma_f32_16x16x32_bf16 v[90:93], v[160:163], v[200:203], v[90:93]
	v_mfma_f32_16x16x32_bf16 v[78:81], v[152:155], v[218:221], v[78:81]
	v_mfma_f32_16x16x32_bf16 v[74:77], v[160:163], v[218:221], v[74:77]
	v_mfma_f32_16x16x32_bf16 v[118:121], v[164:167], v[180:183], v[118:121]
	v_mfma_f32_16x16x32_bf16 v[114:117], v[172:175], v[180:183], v[114:117]
	v_mfma_f32_16x16x32_bf16 v[102:105], v[164:167], v[188:191], v[102:105]
	v_mfma_f32_16x16x32_bf16 v[98:101], v[172:175], v[188:191], v[98:101]
	v_mfma_f32_16x16x32_bf16 v[86:89], v[164:167], v[196:199], v[86:89]
	v_mfma_f32_16x16x32_bf16 v[82:85], v[172:175], v[196:199], v[82:85]
	v_mfma_f32_16x16x32_bf16 v[70:73], v[164:167], v[204:207], v[70:73]
	v_mfma_f32_16x16x32_bf16 v[66:69], v[172:175], v[204:207], v[66:69]
	v_mfma_f32_16x16x32_bf16 v[118:121], v[168:171], v[184:187], v[118:121]
	v_mfma_f32_16x16x32_bf16 v[114:117], v[176:179], v[184:187], v[114:117]
	v_mfma_f32_16x16x32_bf16 v[102:105], v[168:171], v[192:195], v[102:105]
	v_mfma_f32_16x16x32_bf16 v[98:101], v[176:179], v[192:195], v[98:101]
	v_mfma_f32_16x16x32_bf16 v[86:89], v[168:171], v[200:203], v[86:89]
	v_mfma_f32_16x16x32_bf16 v[82:85], v[176:179], v[200:203], v[82:85]
	v_mfma_f32_16x16x32_bf16 v[70:73], v[168:171], v[218:221], v[70:73]
	v_mfma_f32_16x16x32_bf16 v[66:69], v[176:179], v[218:221], v[66:69]
	s_setprio 0
	s_barrier
	s_add_i32 s52, s52, s8
	v_lshl_add_u64 v[144:145], s[38:39], 0, v[0:1]
	s_mov_b32 m0, s52
	ds_read_b128 v[180:183], v150 offset:16384
	ds_read_b128 v[184:187], v150 offset:17408
	ds_read_b128 v[188:191], v150 offset:18432
	ds_read_b128 v[192:195], v150 offset:19456
	ds_read_b128 v[196:199], v150 offset:20480
	ds_read_b128 v[200:203], v150 offset:21504
	ds_read_b128 v[204:207], v150 offset:22528
	ds_read_b128 v[218:221], v150 offset:23552
	global_load_lds_dwordx4 v[144:145], off
	s_add_i32 m0, s52, 0x2000
	s_add_u32 s52, s38, 0x80000
	v_lshl_add_u64 v[208:209], s[38:39], 0, v[134:135]
	s_addc_u32 s53, s39, 0
	s_add_i32 s12, s12, s8
	global_load_lds_dwordx4 v[208:209], off
	v_lshl_add_u64 v[222:223], s[52:53], 0, v[0:1]
	s_mov_b32 m0, s12
	v_lshl_add_u64 v[224:225], s[50:51], 0, v[132:133]
	global_load_lds_dwordx4 v[222:223], off
	v_lshl_add_u64 v[222:223], s[52:53], 0, v[134:135]
	s_add_i32 m0, s12, 0x2000
	s_nop 0
	global_load_lds_dwordx4 v[222:223], off
	v_lshl_add_u64 v[222:223], s[50:51], 0, v[130:131]
	s_mov_b32 m0, s20
	s_nop 0
	global_load_lds_dwordx4 v[222:223], off
	s_mov_b32 m0, s21
	s_nop 0
	global_load_lds_dwordx4 v[224:225], off
	s_waitcnt vmcnt(8)
	s_waitcnt lgkmcnt(0)
	s_barrier
	s_setprio 1
	s_waitcnt lgkmcnt(0)
	v_mfma_f32_16x16x32_bf16 v[62:65], v[140:143], v[180:183], v[62:65]
	v_mfma_f32_16x16x32_bf16 v[58:61], v[156:159], v[180:183], v[58:61]
	v_mfma_f32_16x16x32_bf16 v[46:49], v[140:143], v[188:191], v[46:49]
	v_mfma_f32_16x16x32_bf16 v[42:45], v[156:159], v[188:191], v[42:45]
	v_mfma_f32_16x16x32_bf16 v[30:33], v[140:143], v[196:199], v[30:33]
	v_mfma_f32_16x16x32_bf16 v[26:29], v[156:159], v[196:199], v[26:29]
	v_mfma_f32_16x16x32_bf16 v[14:17], v[140:143], v[204:207], v[14:17]
	v_mfma_f32_16x16x32_bf16 v[10:13], v[156:159], v[204:207], v[10:13]
	v_mfma_f32_16x16x32_bf16 v[62:65], v[152:155], v[184:187], v[62:65]
	v_mfma_f32_16x16x32_bf16 v[58:61], v[160:163], v[184:187], v[58:61]
	v_mfma_f32_16x16x32_bf16 v[46:49], v[152:155], v[192:195], v[46:49]
	v_mfma_f32_16x16x32_bf16 v[42:45], v[160:163], v[192:195], v[42:45]
	v_mfma_f32_16x16x32_bf16 v[30:33], v[152:155], v[200:203], v[30:33]
	v_mfma_f32_16x16x32_bf16 v[26:29], v[160:163], v[200:203], v[26:29]
	v_mfma_f32_16x16x32_bf16 v[14:17], v[152:155], v[218:221], v[14:17]
	v_mfma_f32_16x16x32_bf16 v[10:13], v[160:163], v[218:221], v[10:13]
	v_mfma_f32_16x16x32_bf16 v[54:57], v[164:167], v[180:183], v[54:57]
	v_mfma_f32_16x16x32_bf16 v[50:53], v[172:175], v[180:183], v[50:53]
	v_mfma_f32_16x16x32_bf16 v[38:41], v[164:167], v[188:191], v[38:41]
	v_mfma_f32_16x16x32_bf16 v[34:37], v[172:175], v[188:191], v[34:37]
	v_mfma_f32_16x16x32_bf16 v[22:25], v[164:167], v[196:199], v[22:25]
	v_mfma_f32_16x16x32_bf16 v[18:21], v[172:175], v[196:199], v[18:21]
	v_mfma_f32_16x16x32_bf16 v[6:9], v[164:167], v[204:207], v[6:9]
	v_mfma_f32_16x16x32_bf16 v[2:5], v[172:175], v[204:207], v[2:5]
	v_mfma_f32_16x16x32_bf16 v[54:57], v[168:171], v[184:187], v[54:57]
	v_mfma_f32_16x16x32_bf16 v[50:53], v[176:179], v[184:187], v[50:53]
	v_mfma_f32_16x16x32_bf16 v[38:41], v[168:171], v[192:195], v[38:41]
	v_mfma_f32_16x16x32_bf16 v[34:37], v[176:179], v[192:195], v[34:37]
	v_mfma_f32_16x16x32_bf16 v[22:25], v[168:171], v[200:203], v[22:25]
	v_mfma_f32_16x16x32_bf16 v[18:21], v[176:179], v[200:203], v[18:21]
	v_mfma_f32_16x16x32_bf16 v[6:9], v[168:171], v[218:221], v[6:9]
	v_mfma_f32_16x16x32_bf16 v[2:5], v[176:179], v[218:221], v[2:5]
	s_setprio 0
	s_barrier
	s_add_i32 s12, 0, 0x18000
	v_add_u32_e32 v151, s12, v147
	s_add_i32 s52, 0, 0x1c000
	ds_read_b128 v[140:143], v151
	ds_read_b128 v[152:155], v151 offset:1024
	ds_read_b128 v[156:159], v151 offset:2048
	ds_read_b128 v[160:163], v151 offset:3072
	v_add_u32_e32 v151, s52, v147
	ds_read_b128 v[164:167], v151
	ds_read_b128 v[168:171], v151 offset:1024
	ds_read_b128 v[172:175], v151 offset:2048
	ds_read_b128 v[176:179], v151 offset:3072
	s_add_u32 s50, s50, 0x80000
	s_addc_u32 s51, s51, 0
	s_mov_b32 m0, s22
	v_lshl_add_u64 v[232:233], s[50:51], 0, v[130:131]
	ds_read_b128 v[180:183], v150 offset:32768
	ds_read_b128 v[184:187], v150 offset:33792
	ds_read_b128 v[188:191], v150 offset:34816
	ds_read_b128 v[192:195], v150 offset:35840
	ds_read_b128 v[196:199], v150 offset:36864
	ds_read_b128 v[200:203], v150 offset:37888
	ds_read_b128 v[204:207], v150 offset:38912
	ds_read_b128 v[218:221], v150 offset:39936
	global_load_lds_dwordx4 v[232:233], off
	v_lshl_add_u64 v[232:233], s[50:51], 0, v[132:133]
	s_mov_b32 m0, s23
	s_nop 0
	global_load_lds_dwordx4 v[232:233], off
	s_waitcnt vmcnt(8)
	s_waitcnt lgkmcnt(0)
	s_barrier
	s_setprio 1
	s_waitcnt lgkmcnt(0)
	v_mfma_f32_16x16x32_bf16 v[126:129], v[140:143], v[180:183], v[126:129]
	v_mfma_f32_16x16x32_bf16 v[122:125], v[156:159], v[180:183], v[122:125]
	v_mfma_f32_16x16x32_bf16 v[110:113], v[140:143], v[188:191], v[110:113]
	v_mfma_f32_16x16x32_bf16 v[106:109], v[156:159], v[188:191], v[106:109]
	v_mfma_f32_16x16x32_bf16 v[94:97], v[140:143], v[196:199], v[94:97]
	v_mfma_f32_16x16x32_bf16 v[90:93], v[156:159], v[196:199], v[90:93]
	v_mfma_f32_16x16x32_bf16 v[78:81], v[140:143], v[204:207], v[78:81]
	v_mfma_f32_16x16x32_bf16 v[74:77], v[156:159], v[204:207], v[74:77]
	v_mfma_f32_16x16x32_bf16 v[126:129], v[152:155], v[184:187], v[126:129]
	v_mfma_f32_16x16x32_bf16 v[122:125], v[160:163], v[184:187], v[122:125]
	v_mfma_f32_16x16x32_bf16 v[110:113], v[152:155], v[192:195], v[110:113]
	v_mfma_f32_16x16x32_bf16 v[106:109], v[160:163], v[192:195], v[106:109]
	v_mfma_f32_16x16x32_bf16 v[94:97], v[152:155], v[200:203], v[94:97]
	v_mfma_f32_16x16x32_bf16 v[90:93], v[160:163], v[200:203], v[90:93]
	v_mfma_f32_16x16x32_bf16 v[78:81], v[152:155], v[218:221], v[78:81]
	v_mfma_f32_16x16x32_bf16 v[74:77], v[160:163], v[218:221], v[74:77]
	v_mfma_f32_16x16x32_bf16 v[118:121], v[164:167], v[180:183], v[118:121]
	v_mfma_f32_16x16x32_bf16 v[114:117], v[172:175], v[180:183], v[114:117]
	v_mfma_f32_16x16x32_bf16 v[102:105], v[164:167], v[188:191], v[102:105]
	v_mfma_f32_16x16x32_bf16 v[98:101], v[172:175], v[188:191], v[98:101]
	v_mfma_f32_16x16x32_bf16 v[86:89], v[164:167], v[196:199], v[86:89]
	v_mfma_f32_16x16x32_bf16 v[82:85], v[172:175], v[196:199], v[82:85]
	v_mfma_f32_16x16x32_bf16 v[70:73], v[164:167], v[204:207], v[70:73]
	v_mfma_f32_16x16x32_bf16 v[66:69], v[172:175], v[204:207], v[66:69]
	v_mfma_f32_16x16x32_bf16 v[118:121], v[168:171], v[184:187], v[118:121]
	v_mfma_f32_16x16x32_bf16 v[114:117], v[176:179], v[184:187], v[114:117]
	v_mfma_f32_16x16x32_bf16 v[102:105], v[168:171], v[192:195], v[102:105]
	v_mfma_f32_16x16x32_bf16 v[98:101], v[176:179], v[192:195], v[98:101]
	v_mfma_f32_16x16x32_bf16 v[86:89], v[168:171], v[200:203], v[86:89]
	v_mfma_f32_16x16x32_bf16 v[82:85], v[176:179], v[200:203], v[82:85]
	v_mfma_f32_16x16x32_bf16 v[70:73], v[168:171], v[218:221], v[70:73]
	v_mfma_f32_16x16x32_bf16 v[66:69], v[176:179], v[218:221], v[66:69]
	s_setprio 0
	s_barrier
	s_add_i32 s12, s12, s8
	v_lshl_add_u64 v[144:145], v[144:145], 0, s[16:17]
	s_mov_b32 m0, s12
	ds_read_b128 v[180:183], v150 offset:49152
	ds_read_b128 v[184:187], v150 offset:50176
	ds_read_b128 v[188:191], v150 offset:51200
	ds_read_b128 v[192:195], v150 offset:52224
	ds_read_b128 v[196:199], v150 offset:53248
	ds_read_b128 v[200:203], v150 offset:54272
	ds_read_b128 v[204:207], v150 offset:55296
	ds_read_b128 v[218:221], v150 offset:56320
	global_load_lds_dwordx4 v[144:145], off
	s_add_i32 m0, s12, 0x2000
	s_add_u32 s38, s38, 0x80080
	v_lshl_add_u64 v[144:145], v[208:209], 0, s[16:17]
	s_addc_u32 s39, s39, 0
	s_add_i32 s12, s52, s8
	global_load_lds_dwordx4 v[144:145], off
	v_lshl_add_u64 v[144:145], s[38:39], 0, v[0:1]
	s_mov_b32 m0, s12
	s_nop 0
	global_load_lds_dwordx4 v[144:145], off
	v_lshl_add_u64 v[144:145], s[38:39], 0, v[134:135]
	s_add_i32 m0, s12, 0x2000
	s_nop 0
	global_load_lds_dwordx4 v[144:145], off
	v_lshl_add_u64 v[144:145], v[222:223], 0, s[16:17]
	s_mov_b32 m0, s26
	s_nop 0
	global_load_lds_dwordx4 v[144:145], off
	v_lshl_add_u64 v[144:145], v[224:225], 0, s[16:17]
	s_mov_b32 m0, s27
	s_nop 0
	global_load_lds_dwordx4 v[144:145], off
	s_waitcnt vmcnt(8)
	s_waitcnt lgkmcnt(0)
	s_barrier
	s_setprio 1
	s_waitcnt lgkmcnt(0)
	v_mfma_f32_16x16x32_bf16 v[62:65], v[140:143], v[180:183], v[62:65]
	v_mfma_f32_16x16x32_bf16 v[58:61], v[156:159], v[180:183], v[58:61]
	v_mfma_f32_16x16x32_bf16 v[46:49], v[140:143], v[188:191], v[46:49]
	v_mfma_f32_16x16x32_bf16 v[42:45], v[156:159], v[188:191], v[42:45]
	v_mfma_f32_16x16x32_bf16 v[30:33], v[140:143], v[196:199], v[30:33]
	v_mfma_f32_16x16x32_bf16 v[26:29], v[156:159], v[196:199], v[26:29]
	v_mfma_f32_16x16x32_bf16 v[14:17], v[140:143], v[204:207], v[14:17]
	v_mfma_f32_16x16x32_bf16 v[10:13], v[156:159], v[204:207], v[10:13]
	v_mfma_f32_16x16x32_bf16 v[62:65], v[152:155], v[184:187], v[62:65]
	v_mfma_f32_16x16x32_bf16 v[58:61], v[160:163], v[184:187], v[58:61]
	v_mfma_f32_16x16x32_bf16 v[46:49], v[152:155], v[192:195], v[46:49]
	v_mfma_f32_16x16x32_bf16 v[42:45], v[160:163], v[192:195], v[42:45]
	v_mfma_f32_16x16x32_bf16 v[30:33], v[152:155], v[200:203], v[30:33]
	v_mfma_f32_16x16x32_bf16 v[26:29], v[160:163], v[200:203], v[26:29]
	v_mfma_f32_16x16x32_bf16 v[14:17], v[152:155], v[218:221], v[14:17]
	v_mfma_f32_16x16x32_bf16 v[10:13], v[160:163], v[218:221], v[10:13]
	v_mfma_f32_16x16x32_bf16 v[54:57], v[164:167], v[180:183], v[54:57]
	v_mfma_f32_16x16x32_bf16 v[50:53], v[172:175], v[180:183], v[50:53]
	v_mfma_f32_16x16x32_bf16 v[38:41], v[164:167], v[188:191], v[38:41]
	v_mfma_f32_16x16x32_bf16 v[34:37], v[172:175], v[188:191], v[34:37]
	v_mfma_f32_16x16x32_bf16 v[22:25], v[164:167], v[196:199], v[22:25]
	v_mfma_f32_16x16x32_bf16 v[18:21], v[172:175], v[196:199], v[18:21]
	v_mfma_f32_16x16x32_bf16 v[6:9], v[164:167], v[204:207], v[6:9]
	v_mfma_f32_16x16x32_bf16 v[2:5], v[172:175], v[204:207], v[2:5]
	v_mfma_f32_16x16x32_bf16 v[54:57], v[168:171], v[184:187], v[54:57]
	v_mfma_f32_16x16x32_bf16 v[50:53], v[176:179], v[184:187], v[50:53]
	v_mfma_f32_16x16x32_bf16 v[38:41], v[168:171], v[192:195], v[38:41]
	v_mfma_f32_16x16x32_bf16 v[34:37], v[176:179], v[192:195], v[34:37]
	v_mfma_f32_16x16x32_bf16 v[22:25], v[168:171], v[200:203], v[22:25]
	v_mfma_f32_16x16x32_bf16 v[18:21], v[176:179], v[200:203], v[18:21]
	v_mfma_f32_16x16x32_bf16 v[6:9], v[168:171], v[218:221], v[6:9]
	v_mfma_f32_16x16x32_bf16 v[2:5], v[176:179], v[218:221], v[2:5]
	s_setprio 0
	s_barrier
	s_add_i32 s49, s49, 2
	s_add_u32 s4, s4, 0x100
	s_addc_u32 s5, s5, 0
	s_add_u32 s37, s37, 0x100
	s_addc_u32 s43, s43, 0
	s_cmp_gt_u32 s49, 29
	s_cbranch_scc0 .LBB0_1337
	s_and_b64 vcc, exec, s[30:31]
	s_cbranch_vccz .LBB0_1340
	s_barrier

.LBB0_1422:
	s_add_u32 s38, s4, 0x100
	s_addc_u32 s39, s5, 0
	s_add_i32 s12, 0, 0x10000
	s_cmpk_eq_i32 s57, 0x7c
	s_cselect_b32 s63, s10, s39
	s_cselect_b32 s62, s28, s38
	s_cselect_b32 s61, s29, s51
	s_cselect_b32 s60, s35, s49
	s_add_i32 s59, 0, 0x14000
	v_add_u32_e32 v138, s12, v232
	v_add_u32_e32 v158, s59, v232
	ds_read_b128 v[126:129], v138
	ds_read_b128 v[130:133], v138 offset:1024
	ds_read_b128 v[134:137], v138 offset:2048
	ds_read_b128 v[138:141], v138 offset:3072
	ds_read_b128 v[146:149], v158
	ds_read_b128 v[150:153], v158 offset:1024
	ds_read_b128 v[154:157], v158 offset:2048
	ds_read_b128 v[158:161], v158 offset:3072
	v_lshl_add_u64 v[200:201], s[4:5], 0, v[192:193]
	s_add_i32 m0, s15, 0xc000
	ds_read_b128 v[162:165], v234
	ds_read_b128 v[166:169], v234 offset:1024
	ds_read_b128 v[170:173], v234 offset:2048
	ds_read_b128 v[174:177], v234 offset:3072
	ds_read_b128 v[178:181], v234 offset:4096
	ds_read_b128 v[182:185], v234 offset:5120
	ds_read_b128 v[186:189], v234 offset:6144
	ds_read_b128 v[196:199], v234 offset:7168
	global_load_lds_dwordx4 v[200:201], off
	v_lshl_add_u64 v[200:201], s[4:5], 0, v[194:195]
	s_add_i32 m0, s15, 0xe000
	s_nop 0
	global_load_lds_dwordx4 v[200:201], off
	s_waitcnt vmcnt(8)
	s_waitcnt lgkmcnt(0)
	s_barrier
	s_setprio 1
	s_waitcnt lgkmcnt(0)
	v_mfma_f32_16x16x32_bf16 v[142:145], v[126:129], v[162:165], v[142:145]
	v_mfma_f32_16x16x32_bf16 v[122:125], v[134:137], v[162:165], v[122:125]
	v_mfma_f32_16x16x32_bf16 v[110:113], v[126:129], v[170:173], v[110:113]
	v_mfma_f32_16x16x32_bf16 v[106:109], v[134:137], v[170:173], v[106:109]
	v_mfma_f32_16x16x32_bf16 v[94:97], v[126:129], v[178:181], v[94:97]
	v_mfma_f32_16x16x32_bf16 v[90:93], v[134:137], v[178:181], v[90:93]
	v_mfma_f32_16x16x32_bf16 v[78:81], v[126:129], v[186:189], v[78:81]
	v_mfma_f32_16x16x32_bf16 v[74:77], v[134:137], v[186:189], v[74:77]
	v_mfma_f32_16x16x32_bf16 v[142:145], v[130:133], v[166:169], v[142:145]
	v_mfma_f32_16x16x32_bf16 v[122:125], v[138:141], v[166:169], v[122:125]
	v_mfma_f32_16x16x32_bf16 v[110:113], v[130:133], v[174:177], v[110:113]
	v_mfma_f32_16x16x32_bf16 v[106:109], v[138:141], v[174:177], v[106:109]
	v_mfma_f32_16x16x32_bf16 v[94:97], v[130:133], v[182:185], v[94:97]
	v_mfma_f32_16x16x32_bf16 v[90:93], v[138:141], v[182:185], v[90:93]
	v_mfma_f32_16x16x32_bf16 v[78:81], v[130:133], v[196:199], v[78:81]
	v_mfma_f32_16x16x32_bf16 v[74:77], v[138:141], v[196:199], v[74:77]
	v_mfma_f32_16x16x32_bf16 v[118:121], v[146:149], v[162:165], v[118:121]
	v_mfma_f32_16x16x32_bf16 v[114:117], v[154:157], v[162:165], v[114:117]
	v_mfma_f32_16x16x32_bf16 v[102:105], v[146:149], v[170:173], v[102:105]
	v_mfma_f32_16x16x32_bf16 v[98:101], v[154:157], v[170:173], v[98:101]
	v_mfma_f32_16x16x32_bf16 v[86:89], v[146:149], v[178:181], v[86:89]
	v_mfma_f32_16x16x32_bf16 v[82:85], v[154:157], v[178:181], v[82:85]
	v_mfma_f32_16x16x32_bf16 v[70:73], v[146:149], v[186:189], v[70:73]
	v_mfma_f32_16x16x32_bf16 v[66:69], v[154:157], v[186:189], v[66:69]
	v_mfma_f32_16x16x32_bf16 v[118:121], v[150:153], v[166:169], v[118:121]
	v_mfma_f32_16x16x32_bf16 v[114:117], v[158:161], v[166:169], v[114:117]
	v_mfma_f32_16x16x32_bf16 v[102:105], v[150:153], v[174:177], v[102:105]
	v_mfma_f32_16x16x32_bf16 v[98:101], v[158:161], v[174:177], v[98:101]
	v_mfma_f32_16x16x32_bf16 v[86:89], v[150:153], v[182:185], v[86:89]
	v_mfma_f32_16x16x32_bf16 v[82:85], v[158:161], v[182:185], v[82:85]
	v_mfma_f32_16x16x32_bf16 v[70:73], v[150:153], v[196:199], v[70:73]
	v_mfma_f32_16x16x32_bf16 v[66:69], v[158:161], v[196:199], v[66:69]
	s_setprio 0
	s_barrier
	s_add_i32 s4, s12, s14
	v_lshl_add_u64 v[200:201], s[60:61], 0, v[0:1]
	s_mov_b32 m0, s4
	ds_read_b128 v[162:165], v234 offset:16384
	ds_read_b128 v[166:169], v234 offset:17408
	ds_read_b128 v[170:173], v234 offset:18432
	ds_read_b128 v[174:177], v234 offset:19456
	ds_read_b128 v[178:181], v234 offset:20480
	ds_read_b128 v[182:185], v234 offset:21504
	ds_read_b128 v[186:189], v234 offset:22528
	ds_read_b128 v[196:199], v234 offset:23552
	global_load_lds_dwordx4 v[200:201], off
	s_add_i32 m0, s4, 0x2000
	s_add_u32 s4, s60, 0x200000
	v_lshl_add_u64 v[202:203], s[60:61], 0, v[190:191]
	s_addc_u32 s5, s61, 0
	s_add_i32 s12, s59, s14
	global_load_lds_dwordx4 v[202:203], off
	v_lshl_add_u64 v[204:205], s[4:5], 0, v[0:1]
	s_mov_b32 m0, s12
	v_lshl_add_u64 v[206:207], s[62:63], 0, v[190:191]
	global_load_lds_dwordx4 v[204:205], off
	v_lshl_add_u64 v[204:205], s[4:5], 0, v[190:191]
	s_add_i32 m0, s12, 0x2000
	s_nop 0
	global_load_lds_dwordx4 v[204:205], off
	v_lshl_add_u64 v[204:205], s[62:63], 0, v[0:1]
	s_mov_b32 m0, s15
	s_nop 0
	global_load_lds_dwordx4 v[204:205], off
	s_mov_b32 m0, s20
	s_nop 0
	global_load_lds_dwordx4 v[206:207], off
	s_waitcnt vmcnt(8)
	s_waitcnt lgkmcnt(0)
	s_barrier
	s_setprio 1
	s_waitcnt lgkmcnt(0)
	v_mfma_f32_16x16x32_bf16 v[62:65], v[126:129], v[162:165], v[62:65]
	v_mfma_f32_16x16x32_bf16 v[58:61], v[134:137], v[162:165], v[58:61]
	v_mfma_f32_16x16x32_bf16 v[46:49], v[126:129], v[170:173], v[46:49]
	v_mfma_f32_16x16x32_bf16 v[42:45], v[134:137], v[170:173], v[42:45]
	v_mfma_f32_16x16x32_bf16 v[30:33], v[126:129], v[178:181], v[30:33]
	v_mfma_f32_16x16x32_bf16 v[26:29], v[134:137], v[178:181], v[26:29]
	v_mfma_f32_16x16x32_bf16 v[14:17], v[126:129], v[186:189], v[14:17]
	v_mfma_f32_16x16x32_bf16 v[10:13], v[134:137], v[186:189], v[10:13]
	v_mfma_f32_16x16x32_bf16 v[62:65], v[130:133], v[166:169], v[62:65]
	v_mfma_f32_16x16x32_bf16 v[58:61], v[138:141], v[166:169], v[58:61]
	v_mfma_f32_16x16x32_bf16 v[46:49], v[130:133], v[174:177], v[46:49]
	v_mfma_f32_16x16x32_bf16 v[42:45], v[138:141], v[174:177], v[42:45]
	v_mfma_f32_16x16x32_bf16 v[30:33], v[130:133], v[182:185], v[30:33]
	v_mfma_f32_16x16x32_bf16 v[26:29], v[138:141], v[182:185], v[26:29]
	v_mfma_f32_16x16x32_bf16 v[14:17], v[130:133], v[196:199], v[14:17]
	v_mfma_f32_16x16x32_bf16 v[10:13], v[138:141], v[196:199], v[10:13]
	v_mfma_f32_16x16x32_bf16 v[54:57], v[146:149], v[162:165], v[54:57]
	v_mfma_f32_16x16x32_bf16 v[50:53], v[154:157], v[162:165], v[50:53]
	v_mfma_f32_16x16x32_bf16 v[38:41], v[146:149], v[170:173], v[38:41]
	v_mfma_f32_16x16x32_bf16 v[34:37], v[154:157], v[170:173], v[34:37]
	v_mfma_f32_16x16x32_bf16 v[22:25], v[146:149], v[178:181], v[22:25]
	v_mfma_f32_16x16x32_bf16 v[18:21], v[154:157], v[178:181], v[18:21]
	v_mfma_f32_16x16x32_bf16 v[6:9], v[146:149], v[186:189], v[6:9]
	v_mfma_f32_16x16x32_bf16 v[2:5], v[154:157], v[186:189], v[2:5]
	v_mfma_f32_16x16x32_bf16 v[54:57], v[150:153], v[166:169], v[54:57]
	v_mfma_f32_16x16x32_bf16 v[50:53], v[158:161], v[166:169], v[50:53]
	v_mfma_f32_16x16x32_bf16 v[38:41], v[150:153], v[174:177], v[38:41]
	v_mfma_f32_16x16x32_bf16 v[34:37], v[158:161], v[174:177], v[34:37]
	v_mfma_f32_16x16x32_bf16 v[22:25], v[150:153], v[182:185], v[22:25]
	v_mfma_f32_16x16x32_bf16 v[18:21], v[158:161], v[182:185], v[18:21]
	v_mfma_f32_16x16x32_bf16 v[6:9], v[150:153], v[196:199], v[6:9]
	v_mfma_f32_16x16x32_bf16 v[2:5], v[158:161], v[196:199], v[2:5]
	s_setprio 0
	s_barrier
	s_add_i32 s12, 0, 0x18000
	s_add_i32 s59, 0, 0x1c000
	v_add_u32_e32 v138, s12, v232
	v_add_u32_e32 v158, s59, v232
	ds_read_b128 v[126:129], v138
	ds_read_b128 v[130:133], v138 offset:1024
	ds_read_b128 v[134:137], v138 offset:2048
	ds_read_b128 v[138:141], v138 offset:3072
	ds_read_b128 v[146:149], v158
	ds_read_b128 v[150:153], v158 offset:1024
	ds_read_b128 v[154:157], v158 offset:2048
	ds_read_b128 v[158:161], v158 offset:3072
	s_add_u32 s4, s62, 0x200000
	s_addc_u32 s5, s63, 0
	s_mov_b32 m0, s21
	v_lshl_add_u64 v[208:209], s[4:5], 0, v[0:1]
	ds_read_b128 v[162:165], v234 offset:32768
	ds_read_b128 v[166:169], v234 offset:33792
	ds_read_b128 v[170:173], v234 offset:34816
	ds_read_b128 v[174:177], v234 offset:35840
	ds_read_b128 v[178:181], v234 offset:36864
	ds_read_b128 v[182:185], v234 offset:37888
	ds_read_b128 v[186:189], v234 offset:38912
	ds_read_b128 v[196:199], v234 offset:39936
	global_load_lds_dwordx4 v[208:209], off
	v_lshl_add_u64 v[208:209], s[4:5], 0, v[190:191]
	s_mov_b32 m0, s22
	s_nop 0
	global_load_lds_dwordx4 v[208:209], off
	s_waitcnt vmcnt(8)
	s_waitcnt lgkmcnt(0)
	s_barrier
	s_setprio 1
	s_waitcnt lgkmcnt(0)
	v_mfma_f32_16x16x32_bf16 v[142:145], v[126:129], v[162:165], v[142:145]
	v_mfma_f32_16x16x32_bf16 v[122:125], v[134:137], v[162:165], v[122:125]
	v_mfma_f32_16x16x32_bf16 v[110:113], v[126:129], v[170:173], v[110:113]
	v_mfma_f32_16x16x32_bf16 v[106:109], v[134:137], v[170:173], v[106:109]
	v_mfma_f32_16x16x32_bf16 v[94:97], v[126:129], v[178:181], v[94:97]
	v_mfma_f32_16x16x32_bf16 v[90:93], v[134:137], v[178:181], v[90:93]
	v_mfma_f32_16x16x32_bf16 v[78:81], v[126:129], v[186:189], v[78:81]
	v_mfma_f32_16x16x32_bf16 v[74:77], v[134:137], v[186:189], v[74:77]
	v_mfma_f32_16x16x32_bf16 v[142:145], v[130:133], v[166:169], v[142:145]
	v_mfma_f32_16x16x32_bf16 v[122:125], v[138:141], v[166:169], v[122:125]
	v_mfma_f32_16x16x32_bf16 v[110:113], v[130:133], v[174:177], v[110:113]
	v_mfma_f32_16x16x32_bf16 v[106:109], v[138:141], v[174:177], v[106:109]
	v_mfma_f32_16x16x32_bf16 v[94:97], v[130:133], v[182:185], v[94:97]
	v_mfma_f32_16x16x32_bf16 v[90:93], v[138:141], v[182:185], v[90:93]
	v_mfma_f32_16x16x32_bf16 v[78:81], v[130:133], v[196:199], v[78:81]
	v_mfma_f32_16x16x32_bf16 v[74:77], v[138:141], v[196:199], v[74:77]
	v_mfma_f32_16x16x32_bf16 v[118:121], v[146:149], v[162:165], v[118:121]
	v_mfma_f32_16x16x32_bf16 v[114:117], v[154:157], v[162:165], v[114:117]
	v_mfma_f32_16x16x32_bf16 v[102:105], v[146:149], v[170:173], v[102:105]
	v_mfma_f32_16x16x32_bf16 v[98:101], v[154:157], v[170:173], v[98:101]
	v_mfma_f32_16x16x32_bf16 v[86:89], v[146:149], v[178:181], v[86:89]
	v_mfma_f32_16x16x32_bf16 v[82:85], v[154:157], v[178:181], v[82:85]
	v_mfma_f32_16x16x32_bf16 v[70:73], v[146:149], v[186:189], v[70:73]
	v_mfma_f32_16x16x32_bf16 v[66:69], v[154:157], v[186:189], v[66:69]
	v_mfma_f32_16x16x32_bf16 v[118:121], v[150:153], v[166:169], v[118:121]
	v_mfma_f32_16x16x32_bf16 v[114:117], v[158:161], v[166:169], v[114:117]
	v_mfma_f32_16x16x32_bf16 v[102:105], v[150:153], v[174:177], v[102:105]
	v_mfma_f32_16x16x32_bf16 v[98:101], v[158:161], v[174:177], v[98:101]
	v_mfma_f32_16x16x32_bf16 v[86:89], v[150:153], v[182:185], v[86:89]
	v_mfma_f32_16x16x32_bf16 v[82:85], v[158:161], v[182:185], v[82:85]
	v_mfma_f32_16x16x32_bf16 v[70:73], v[150:153], v[196:199], v[70:73]
	v_mfma_f32_16x16x32_bf16 v[66:69], v[158:161], v[196:199], v[66:69]
	s_setprio 0
	s_barrier
	s_add_i32 s4, s12, s14
	v_lshl_add_u64 v[200:201], v[200:201], 0, s[16:17]
	s_mov_b32 m0, s4
	ds_read_b128 v[162:165], v234 offset:49152
	ds_read_b128 v[166:169], v234 offset:50176
	ds_read_b128 v[170:173], v234 offset:51200
	ds_read_b128 v[174:177], v234 offset:52224
	ds_read_b128 v[178:181], v234 offset:53248
	ds_read_b128 v[182:185], v234 offset:54272
	ds_read_b128 v[186:189], v234 offset:55296
	ds_read_b128 v[196:199], v234 offset:56320
	global_load_lds_dwordx4 v[200:201], off
	s_add_i32 m0, s4, 0x2000
	s_add_u32 s4, s60, 0x200080
	v_lshl_add_u64 v[200:201], v[202:203], 0, s[16:17]
	s_addc_u32 s5, s61, 0
	s_add_i32 s12, s59, s14
	global_load_lds_dwordx4 v[200:201], off
	v_lshl_add_u64 v[200:201], s[4:5], 0, v[0:1]
	s_mov_b32 m0, s12
	s_nop 0
	global_load_lds_dwordx4 v[200:201], off
	v_lshl_add_u64 v[200:201], s[4:5], 0, v[190:191]
	s_add_i32 m0, s12, 0x2000
	s_nop 0
	global_load_lds_dwordx4 v[200:201], off
	v_lshl_add_u64 v[200:201], v[204:205], 0, s[16:17]
	s_mov_b32 m0, s26
	s_nop 0
	global_load_lds_dwordx4 v[200:201], off
	v_lshl_add_u64 v[200:201], v[206:207], 0, s[16:17]
	s_mov_b32 m0, s27
	s_nop 0
	global_load_lds_dwordx4 v[200:201], off
	s_waitcnt vmcnt(8)
	s_waitcnt lgkmcnt(0)
	s_barrier
	s_setprio 1
	s_waitcnt lgkmcnt(0)
	v_mfma_f32_16x16x32_bf16 v[62:65], v[126:129], v[162:165], v[62:65]
	v_mfma_f32_16x16x32_bf16 v[58:61], v[134:137], v[162:165], v[58:61]
	v_mfma_f32_16x16x32_bf16 v[46:49], v[126:129], v[170:173], v[46:49]
	v_mfma_f32_16x16x32_bf16 v[42:45], v[134:137], v[170:173], v[42:45]
	v_mfma_f32_16x16x32_bf16 v[30:33], v[126:129], v[178:181], v[30:33]
	v_mfma_f32_16x16x32_bf16 v[26:29], v[134:137], v[178:181], v[26:29]
	v_mfma_f32_16x16x32_bf16 v[14:17], v[126:129], v[186:189], v[14:17]
	v_mfma_f32_16x16x32_bf16 v[10:13], v[134:137], v[186:189], v[10:13]
	v_mfma_f32_16x16x32_bf16 v[62:65], v[130:133], v[166:169], v[62:65]
	v_mfma_f32_16x16x32_bf16 v[58:61], v[138:141], v[166:169], v[58:61]
	v_mfma_f32_16x16x32_bf16 v[46:49], v[130:133], v[174:177], v[46:49]
	v_mfma_f32_16x16x32_bf16 v[42:45], v[138:141], v[174:177], v[42:45]
	v_mfma_f32_16x16x32_bf16 v[30:33], v[130:133], v[182:185], v[30:33]
	v_mfma_f32_16x16x32_bf16 v[26:29], v[138:141], v[182:185], v[26:29]
	v_mfma_f32_16x16x32_bf16 v[14:17], v[130:133], v[196:199], v[14:17]
	v_mfma_f32_16x16x32_bf16 v[10:13], v[138:141], v[196:199], v[10:13]
	v_mfma_f32_16x16x32_bf16 v[54:57], v[146:149], v[162:165], v[54:57]
	v_mfma_f32_16x16x32_bf16 v[50:53], v[154:157], v[162:165], v[50:53]
	v_mfma_f32_16x16x32_bf16 v[38:41], v[146:149], v[170:173], v[38:41]
	v_mfma_f32_16x16x32_bf16 v[34:37], v[154:157], v[170:173], v[34:37]
	v_mfma_f32_16x16x32_bf16 v[22:25], v[146:149], v[178:181], v[22:25]
	v_mfma_f32_16x16x32_bf16 v[18:21], v[154:157], v[178:181], v[18:21]
	v_mfma_f32_16x16x32_bf16 v[6:9], v[146:149], v[186:189], v[6:9]
	v_mfma_f32_16x16x32_bf16 v[2:5], v[154:157], v[186:189], v[2:5]
	v_mfma_f32_16x16x32_bf16 v[54:57], v[150:153], v[166:169], v[54:57]
	v_mfma_f32_16x16x32_bf16 v[50:53], v[158:161], v[166:169], v[50:53]
	v_mfma_f32_16x16x32_bf16 v[38:41], v[150:153], v[174:177], v[38:41]
	v_mfma_f32_16x16x32_bf16 v[34:37], v[158:161], v[174:177], v[34:37]
	v_mfma_f32_16x16x32_bf16 v[22:25], v[150:153], v[182:185], v[22:25]
	v_mfma_f32_16x16x32_bf16 v[18:21], v[158:161], v[182:185], v[18:21]
	v_mfma_f32_16x16x32_bf16 v[6:9], v[150:153], v[196:199], v[6:9]
	v_mfma_f32_16x16x32_bf16 v[2:5], v[158:161], v[196:199], v[2:5]
	s_setprio 0
	s_barrier
	s_add_i32 s57, s57, 2
	s_add_u32 s49, s49, 0x100
	s_addc_u32 s51, s51, 0
	s_cmpk_gt_u32 s57, 0x7d
	s_mov_b64 s[4:5], s[38:39]
	s_cbranch_scc0 .LBB0_1422
	s_and_b64 vcc, exec, s[46:47]
	s_cbranch_vccz .LBB0_1425
	s_barrier
